# all gemm128 K-loops (phases 1,4,5,6) staged with global_load_lds instead of VGPR staging+ds_write; per-load swizzled address kept in the old staging regs, +128 per stage
# speedup vs baseline: 1.0721x; 1.0228x over previous
_Z4megaILin1EEv6Params:
	v_lshrrev_b32_e32 v238, 3, v0
	v_xor_b32_e32 v238, v238, v0
	v_and_b32_e32 v238, 7, v238
	v_and_b32_e32 v239, 7, v0
	v_sub_u32_e32 v238, v238, v239
	v_lshlrev_b32_e32 v238, 4, v238
	v_ashrrev_i32_e32 v239, 31, v238
	v_mov_b32_e32 v242, 0x80
	v_mov_b32_e32 v243, 0
	v_lshrrev_b32_e32 v244, 6, v0
	s_nop 1
	v_readfirstlane_b32 s98, v244
	s_nop 3
	s_lshl_b32 s98, s98, 10
	v_add_co_u32_e32 v240, vcc, 0x400, v238
	s_nop 1
	v_addc_co_u32_e32 v241, vcc, 0, v239, vcc
	s_load_dwordx2 s[54:55], s[0:1], 0xc0
	s_load_dword s72, s[0:1], 0xc8
	s_mov_b32 s96, s2
	s_getreg_b32 s2, hwreg(HW_REG_XCC_ID, 0, 4)
	v_cmp_eq_u32_e64 s[4:5], 0, v0
	s_waitcnt lgkmcnt(0)
	s_add_u32 s46, s54, 0xf33d800
	s_addc_u32 s47, s55, 0
	s_and_b32 s78, s2, 15
	s_mov_b64 s[2:3], exec
	v_writelane_b32 v237, s4, 0
	s_nop 1
	v_writelane_b32 v237, s5, 1
	s_and_b64 s[4:5], s[2:3], s[4:5]
	s_mov_b64 exec, s[4:5]
	s_cbranch_execz .LBB0_3
	s_mov_b64 s[4:5], exec
	v_mbcnt_lo_u32_b32 v1, s4, 0
	v_mbcnt_hi_u32_b32 v1, s5, v1
	v_cmp_eq_u32_e32 vcc, 0, v1
	s_and_b64 s[6:7], exec, vcc
	s_mov_b64 exec, s[6:7]
	s_cbranch_execz .LBB0_3
	s_lshl_b32 s6, s78, 8
	s_bcnt1_i32_b64 s4, s[4:5]
	v_mov_b32_e32 v1, s6
	v_mov_b32_e32 v2, s4
	global_atomic_add v1, v2, s[46:47] offset:1024

.LBB0_122:
	s_lshl_b32 s4, s4, 7
	s_lshl_b32 s2, s5, 7
	s_ashr_i32 s5, s4, 31
	s_lshl_b64 s[6:7], s[4:5], 11
	v_lshl_add_u64 v[104:105], v[98:99], 0, s[6:7]
	v_add_co_u32_e32 v4, vcc, s14, v104
	s_ashr_i32 s3, s2, 31
	s_nop 0
	v_addc_co_u32_e32 v5, vcc, 0, v105, vcc
	v_add_co_u32_e32 v6, vcc, s15, v104
	s_lshl_b64 s[8:9], s[2:3], 11
	s_nop 0
	v_addc_co_u32_e32 v7, vcc, 0, v105, vcc
	s_barrier
	s_add_u32 m0, s98, 0x1000
	v_lshl_add_u64 v[38:39], v[4:5], 0, v[238:239]
	global_load_lds_dwordx4 v[38:39], off
	s_add_u32 m0, s98, 0x2000
	v_lshl_add_u64 v[54:55], v[6:7], 0, v[238:239]
	global_load_lds_dwordx4 v[54:55], off
	v_add_co_u32_e32 v4, vcc, s16, v104
	v_lshl_add_u64 v[2:3], v[100:101], 0, s[8:9]
	s_nop 0
	v_addc_co_u32_e32 v5, vcc, 0, v105, vcc
	v_add_co_u32_e32 v6, vcc, s14, v2
	s_mov_b32 m0, s98
	v_lshl_add_u64 v[42:43], v[104:105], 0, v[238:239]
	global_load_lds_dwordx4 v[42:43], off
	s_add_u32 m0, s98, 0x4000
	v_lshl_add_u64 v[66:67], v[2:3], 0, v[238:239]
	global_load_lds_dwordx4 v[66:67], off
	v_addc_co_u32_e32 v7, vcc, 0, v3, vcc
	s_add_u32 m0, s98, 0x3000
	v_lshl_add_u64 v[62:63], v[4:5], 0, v[238:239]
	global_load_lds_dwordx4 v[62:63], off
	s_add_u32 m0, s98, 0x5000
	v_lshl_add_u64 v[70:71], v[6:7], 0, v[238:239]
	global_load_lds_dwordx4 v[70:71], off
	v_add_co_u32_e32 v4, vcc, s15, v2
	s_mov_b32 s5, 0
	s_nop 0
	v_addc_co_u32_e32 v5, vcc, 0, v3, vcc
	v_add_co_u32_e32 v2, vcc, s16, v2
	s_mov_b64 s[6:7], 0
	s_nop 0
	v_addc_co_u32_e32 v3, vcc, 0, v3, vcc
	s_add_u32 m0, s98, 0x6000
	v_lshl_add_u64 v[74:75], v[4:5], 0, v[238:239]
	global_load_lds_dwordx4 v[74:75], off
	s_add_u32 m0, s98, 0x7000
	v_lshl_add_u64 v[78:79], v[2:3], 0, v[238:239]
	global_load_lds_dwordx4 v[78:79], off
	v_mov_b32_e32 v2, 0
	s_mov_b32 s3, 0
	v_mov_b32_e32 v3, v2
	v_mov_b32_e32 v4, v2
	v_mov_b32_e32 v5, v2
	v_mov_b32_e32 v6, v2
	v_mov_b32_e32 v7, v2
	v_mov_b32_e32 v8, v2
	v_mov_b32_e32 v9, v2
	v_mov_b32_e32 v10, v2
	v_mov_b32_e32 v11, v2
	v_mov_b32_e32 v12, v2
	v_mov_b32_e32 v13, v2
	v_mov_b32_e32 v14, v2
	v_mov_b32_e32 v15, v2
	v_mov_b32_e32 v16, v2
	v_mov_b32_e32 v17, v2
	v_mov_b32_e32 v18, v2
	v_mov_b32_e32 v19, v2
	v_mov_b32_e32 v20, v2
	v_mov_b32_e32 v21, v2
	v_mov_b32_e32 v22, v2
	v_mov_b32_e32 v23, v2
	v_mov_b32_e32 v24, v2
	v_mov_b32_e32 v25, v2
	v_mov_b32_e32 v26, v2
	v_mov_b32_e32 v27, v2
	v_mov_b32_e32 v28, v2
	v_mov_b32_e32 v29, v2
	v_lshl_add_u64 v[106:107], v[102:103], 0, s[8:9]
	v_mov_b32_e32 v30, v2
	v_mov_b32_e32 v31, v2
	v_mov_b32_e32 v32, v2
	v_mov_b32_e32 v33, v2
	v_mov_b32_e32 v34, v2
	v_mov_b32_e32 v35, v2
	v_mov_b32_e32 v36, v2
	v_mov_b32_e32 v37, v2
	v_mov_b32_e32 v46, v2
	v_mov_b32_e32 v47, v2
	v_mov_b32_e32 v48, v2
	v_mov_b32_e32 v49, v2
	v_mov_b32_e32 v50, v2
	v_mov_b32_e32 v51, v2
	v_mov_b32_e32 v52, v2
	v_mov_b32_e32 v53, v2
	v_mov_b32_e32 v58, v2
	v_mov_b32_e32 v59, v2
	v_mov_b32_e32 v60, v2
	v_mov_b32_e32 v61, v2
	v_mov_b32_e32 v82, v2
	v_mov_b32_e32 v83, v2
	v_mov_b32_e32 v84, v2
	v_mov_b32_e32 v85, v2
	v_mov_b32_e32 v86, v2
	v_mov_b32_e32 v87, v2
	v_mov_b32_e32 v88, v2
	v_mov_b32_e32 v89, v2
	v_mov_b32_e32 v90, v2
	v_mov_b32_e32 v91, v2
	v_mov_b32_e32 v92, v2
	v_mov_b32_e32 v93, v2
	v_mov_b32_e32 v94, v2
	v_mov_b32_e32 v95, v2
	v_mov_b32_e32 v96, v2
	v_mov_b32_e32 v97, v2
	s_waitcnt lgkmcnt(0)
	s_waitcnt vmcnt(0)
	s_barrier
	s_branch .LBB0_124
.LBB0_123:
	s_add_u32 s6, s6, 0x80
	s_addc_u32 s7, s7, 0
	s_add_i32 s3, s3, 1
	s_cmpk_lg_i32 s6, 0x800
	s_mov_b32 s5, s8
	s_waitcnt lgkmcnt(0)
	s_waitcnt vmcnt(0)
	s_barrier
	s_cbranch_scc0 .LBB0_114
.LBB0_124:
	s_cmp_gt_u32 s3, 14
	s_cselect_b64 s[8:9], -1, 0
	s_and_b64 vcc, exec, s[8:9]
	s_cbranch_vccnz .LBB0_126
	s_and_b32 s99, s5, 0x8000
	s_xor_b32 s99, s99, 0x8000
	s_add_u32 s99, s99, s98
	s_mov_b32 m0, s99
	v_lshl_add_u64 v[42:43], v[42:43], 0, v[242:243]
	global_load_lds_dwordx4 v[42:43], off
	s_add_u32 m0, s99, 0x1000
	v_lshl_add_u64 v[38:39], v[38:39], 0, v[242:243]
	global_load_lds_dwordx4 v[38:39], off
	s_add_u32 m0, s99, 0x2000
	v_lshl_add_u64 v[54:55], v[54:55], 0, v[242:243]
	global_load_lds_dwordx4 v[54:55], off
	s_add_u32 m0, s99, 0x3000
	v_lshl_add_u64 v[62:63], v[62:63], 0, v[242:243]
	global_load_lds_dwordx4 v[62:63], off
	s_add_u32 m0, s99, 0x4000
	v_lshl_add_u64 v[66:67], v[66:67], 0, v[242:243]
	global_load_lds_dwordx4 v[66:67], off
	s_add_u32 m0, s99, 0x5000
	v_lshl_add_u64 v[70:71], v[70:71], 0, v[242:243]
	global_load_lds_dwordx4 v[70:71], off
	s_add_u32 m0, s99, 0x6000
	v_lshl_add_u64 v[74:75], v[74:75], 0, v[242:243]
	global_load_lds_dwordx4 v[74:75], off
	s_add_u32 m0, s99, 0x7000
	v_lshl_add_u64 v[78:79], v[78:79], 0, v[242:243]
	global_load_lds_dwordx4 v[78:79], off

.LBB0_128:
	s_andn2_b64 vcc, exec, s[10:11]
	s_cbranch_vccnz .LBB0_123
	s_add_i32 s8, s5, 0x8000
	s_and_b32 s5, s8, 0x8000
	v_or_b32_e32 v115, s5, v108
	s_branch .LBB0_123

.LBB0_733:
	s_lshl_b32 s2, s23, 10
	s_and_b32 s2, s2, 0x60000
	v_lshl_add_u64 v[108:109], v[106:107], 0, s[2:3]
	s_lshl_b32 s2, s29, 5
	s_and_b32 s8, s2, 0xffffff80
	s_ashr_i32 s9, s8, 31
	s_lshl_b64 s[10:11], s[8:9], 10
	v_lshl_add_u64 v[2:3], v[100:101], 0, s[10:11]
	v_add_co_u32_e32 v6, vcc, s25, v2
	s_lshl_b32 s2, s29, 7
	s_nop 0
	v_addc_co_u32_e32 v7, vcc, 0, v3, vcc
	v_add_co_u32_e32 v8, vcc, s26, v2
	s_and_b32 s30, s2, 0x180
	s_nop 0
	v_addc_co_u32_e32 v9, vcc, 0, v3, vcc
	s_lshl_b32 s2, s30, 10
	s_barrier
	s_mov_b32 m0, s98
	v_lshl_add_u64 v[66:67], v[2:3], 0, v[238:239]
	global_load_lds_dwordx4 v[66:67], off
	v_add_co_u32_e32 v2, vcc, s27, v2
	v_lshl_add_u64 v[4:5], v[102:103], 0, s[2:3]
	s_nop 0
	v_addc_co_u32_e32 v3, vcc, 0, v3, vcc
	s_add_u32 m0, s98, 0x1000
	v_lshl_add_u64 v[70:71], v[6:7], 0, v[238:239]
	global_load_lds_dwordx4 v[70:71], off
	s_add_u32 m0, s98, 0x2000
	v_lshl_add_u64 v[74:75], v[8:9], 0, v[238:239]
	global_load_lds_dwordx4 v[74:75], off
	s_add_u32 m0, s98, 0x3000
	v_lshl_add_u64 v[78:79], v[2:3], 0, v[238:239]
	global_load_lds_dwordx4 v[78:79], off
	s_add_u32 m0, s98, 0x4000
	v_lshl_add_u64 v[82:83], v[4:5], 0, v[238:239]
	global_load_lds_dwordx4 v[82:83], off
	v_add_co_u32_e32 v2, vcc, s25, v4
	s_and_b32 s12, s21, 0xffffff80
	s_nop 0
	v_addc_co_u32_e32 v3, vcc, 0, v5, vcc
	v_add_co_u32_e32 v6, vcc, s26, v4
	s_ashr_i32 s13, s12, 31
	s_nop 0
	v_addc_co_u32_e32 v7, vcc, 0, v5, vcc
	s_add_u32 m0, s98, 0x5000
	v_lshl_add_u64 v[86:87], v[2:3], 0, v[238:239]
	global_load_lds_dwordx4 v[86:87], off
	s_add_u32 m0, s98, 0x6000
	v_lshl_add_u64 v[90:91], v[6:7], 0, v[238:239]
	global_load_lds_dwordx4 v[90:91], off
	v_add_co_u32_e32 v2, vcc, s27, v4
	s_lshl_b64 s[12:13], s[12:13], 10
	s_nop 0
	v_addc_co_u32_e32 v3, vcc, 0, v5, vcc
	s_add_u32 m0, s98, 0x7000
	v_lshl_add_u64 v[94:95], v[2:3], 0, v[238:239]
	global_load_lds_dwordx4 v[94:95], off
	s_mov_b32 s9, 0
	s_mov_b64 s[10:11], 0
	s_mov_b32 s2, 0
	v_mov_b32_e32 v62, 0
	v_mov_b32_e32 v63, v99
	v_mov_b32_e32 v64, v99
	v_mov_b32_e32 v65, v99
	v_mov_b32_e32 v58, 0
	v_mov_b32_e32 v59, v99
	v_mov_b32_e32 v60, v99
	v_mov_b32_e32 v61, v99
	v_mov_b32_e32 v54, 0
	v_mov_b32_e32 v55, v99
	v_mov_b32_e32 v56, v99
	v_mov_b32_e32 v57, v99
	v_mov_b32_e32 v50, 0
	v_mov_b32_e32 v51, v99
	v_mov_b32_e32 v52, v99
	v_mov_b32_e32 v53, v99
	v_mov_b32_e32 v46, 0
	v_mov_b32_e32 v47, v99
	v_mov_b32_e32 v48, v99
	v_mov_b32_e32 v49, v99
	v_mov_b32_e32 v42, 0
	v_lshl_add_u64 v[110:111], v[104:105], 0, s[12:13]
	v_mov_b32_e32 v43, v99
	v_mov_b32_e32 v44, v99
	v_mov_b32_e32 v45, v99
	v_mov_b32_e32 v38, 0
	v_mov_b32_e32 v39, v99
	v_mov_b32_e32 v40, v99
	v_mov_b32_e32 v41, v99
	v_mov_b32_e32 v34, 0
	v_mov_b32_e32 v35, v99
	v_mov_b32_e32 v36, v99
	v_mov_b32_e32 v37, v99
	v_mov_b32_e32 v30, 0
	v_mov_b32_e32 v31, v99
	v_mov_b32_e32 v32, v99
	v_mov_b32_e32 v33, v99
	v_mov_b32_e32 v26, 0
	v_mov_b32_e32 v27, v99
	v_mov_b32_e32 v28, v99
	v_mov_b32_e32 v29, v99
	v_mov_b32_e32 v22, 0
	v_mov_b32_e32 v23, v99
	v_mov_b32_e32 v24, v99
	v_mov_b32_e32 v25, v99
	v_mov_b32_e32 v18, 0
	v_mov_b32_e32 v19, v99
	v_mov_b32_e32 v20, v99
	v_mov_b32_e32 v21, v99
	v_mov_b32_e32 v14, 0
	v_mov_b32_e32 v15, v99
	v_mov_b32_e32 v16, v99
	v_mov_b32_e32 v17, v99
	v_mov_b32_e32 v10, 0
	v_mov_b32_e32 v11, v99
	v_mov_b32_e32 v12, v99
	v_mov_b32_e32 v13, v99
	v_mov_b32_e32 v6, 0
	v_mov_b32_e32 v7, v99
	v_mov_b32_e32 v8, v99
	v_mov_b32_e32 v9, v99
	v_mov_b32_e32 v2, 0
	v_mov_b32_e32 v3, v99
	v_mov_b32_e32 v4, v99
	v_mov_b32_e32 v5, v99
	s_waitcnt lgkmcnt(0)
	s_waitcnt vmcnt(0)
	s_barrier
	s_branch .LBB0_735
.LBB0_734:
	s_add_u32 s10, s10, 0x80
	s_addc_u32 s11, s11, 0
	s_add_i32 s2, s2, 1
	s_cmpk_lg_i32 s10, 0x400
	s_mov_b32 s9, s12
	s_waitcnt lgkmcnt(0)
	s_waitcnt vmcnt(0)
	s_barrier
	s_cbranch_scc0 .LBB0_732
.LBB0_735:
	s_cmp_gt_u32 s2, 6
	s_cselect_b64 s[12:13], -1, 0
	s_and_b64 vcc, exec, s[12:13]
	s_cbranch_vccnz .LBB0_737
	s_and_b32 s99, s9, 0x8000
	s_xor_b32 s99, s99, 0x8000
	s_add_u32 s99, s99, s98
	s_mov_b32 m0, s99
	v_lshl_add_u64 v[66:67], v[66:67], 0, v[242:243]
	global_load_lds_dwordx4 v[66:67], off
	s_add_u32 m0, s99, 0x1000
	v_lshl_add_u64 v[70:71], v[70:71], 0, v[242:243]
	global_load_lds_dwordx4 v[70:71], off
	s_add_u32 m0, s99, 0x2000
	v_lshl_add_u64 v[74:75], v[74:75], 0, v[242:243]
	global_load_lds_dwordx4 v[74:75], off
	s_add_u32 m0, s99, 0x3000
	v_lshl_add_u64 v[78:79], v[78:79], 0, v[242:243]
	global_load_lds_dwordx4 v[78:79], off
	s_add_u32 m0, s99, 0x4000
	v_lshl_add_u64 v[82:83], v[82:83], 0, v[242:243]
	global_load_lds_dwordx4 v[82:83], off
	s_add_u32 m0, s99, 0x5000
	v_lshl_add_u64 v[86:87], v[86:87], 0, v[242:243]
	global_load_lds_dwordx4 v[86:87], off
	s_add_u32 m0, s99, 0x6000
	v_lshl_add_u64 v[90:91], v[90:91], 0, v[242:243]
	global_load_lds_dwordx4 v[90:91], off
	s_add_u32 m0, s99, 0x7000
	v_lshl_add_u64 v[94:95], v[94:95], 0, v[242:243]
	global_load_lds_dwordx4 v[94:95], off

.LBB0_739:
	s_andn2_b64 vcc, exec, s[14:15]
	s_cbranch_vccnz .LBB0_734
	s_add_i32 s12, s9, 0x8000
	s_and_b32 s9, s12, 0x8000
	v_or_b32_e32 v98, s9, v112
	s_branch .LBB0_734
.LBB0_741:
	s_cmp_lt_i32 s96, s19
	s_cbranch_scc0 .LBB0_751
	s_ashr_i32 s11, s96, 1
	s_add_i32 s18, s18, s11
	s_lshl_b32 s2, s18, 5
	s_lshl_b32 s3, s96, 6
	s_and_b32 s2, s2, 0xffffff80
	s_and_b32 s3, s3, 64
	v_readlane_b32 s68, v237, 35
	s_or_b32 s2, s2, s3
	s_lshl_b32 s3, s18, 7
	v_readlane_b32 s80, v237, 47
	v_readlane_b32 s81, v237, 48
	s_and_b32 s10, s3, 0x180
	s_ashr_i32 s3, s2, 31
	v_readlane_b32 s82, v237, 49
	v_readlane_b32 s83, v237, 50
	s_mov_b64 s[24:25], s[80:81]
	s_lshl_b64 s[4:5], s[2:3], 10
	s_mov_b64 s[26:27], s[82:83]
	s_add_u32 s6, s26, s4
	s_addc_u32 s7, s27, s5
	s_lshl_b32 s3, s10, 10
	v_lshrrev_b32_e32 v8, 3, v0
	s_add_u32 s8, s54, s3
	v_lshlrev_b32_e32 v14, 10, v8
	v_mov_b32_e32 v15, 0
	v_lshlrev_b32_e32 v4, 4, v0
	s_addc_u32 s9, s55, 0
	v_lshl_add_u64 v[2:3], s[6:7], 0, v[14:15]
	v_and_b32_e32 v4, 0x70, v4
	v_mov_b32_e32 v5, v15
	v_lshl_add_u64 v[2:3], v[2:3], 0, v[4:5]
	v_lshl_add_u64 v[6:7], s[8:9], 0, v[14:15]
	s_mov_b32 s3, 0x2400000
	v_lshl_add_u64 v[4:5], v[6:7], 0, v[4:5]
	v_add_co_u32_e32 v6, vcc, s3, v2
	s_mov_b32 s3, 0x2408000
	s_nop 0
	v_addc_co_u32_e32 v7, vcc, 0, v3, vcc
	v_add_co_u32_e32 v2, vcc, s3, v2
	s_mov_b32 s3, 0xed80000
	s_nop 0
	v_addc_co_u32_e32 v3, vcc, 0, v3, vcc
	s_barrier
	s_mov_b32 m0, s98
	v_lshl_add_u64 v[34:35], v[6:7], 0, v[238:239]
	global_load_lds_dwordx4 v[34:35], off
	s_add_u32 m0, s98, 0x1000
	v_lshl_add_u64 v[38:39], v[2:3], 0, v[238:239]
	global_load_lds_dwordx4 v[38:39], off
	v_add_co_u32_e32 v2, vcc, s3, v4
	s_mov_b32 s3, 0xed88000
	s_nop 0
	v_addc_co_u32_e32 v3, vcc, 0, v5, vcc
	v_add_co_u32_e32 v6, vcc, s3, v4
	s_mov_b32 s3, 0xed90000
	s_nop 0
	v_addc_co_u32_e32 v7, vcc, 0, v5, vcc
	s_add_u32 m0, s98, 0x4000
	v_lshl_add_u64 v[42:43], v[2:3], 0, v[238:239]
	global_load_lds_dwordx4 v[42:43], off
	s_add_u32 m0, s98, 0x5000
	v_lshl_add_u64 v[46:47], v[6:7], 0, v[238:239]
	global_load_lds_dwordx4 v[46:47], off
	v_add_co_u32_e32 v2, vcc, s3, v4
	s_mov_b32 s3, 0xed98000
	s_nop 0
	v_addc_co_u32_e32 v3, vcc, 0, v5, vcc
	v_add_co_u32_e32 v4, vcc, s3, v4
	v_lshlrev_b32_e32 v6, 7, v0
	s_nop 0
	v_addc_co_u32_e32 v5, vcc, 0, v5, vcc
	s_add_u32 m0, s98, 0x6000
	v_lshl_add_u64 v[50:51], v[2:3], 0, v[238:239]
	global_load_lds_dwordx4 v[50:51], off
	s_add_u32 m0, s98, 0x7000
	v_lshl_add_u64 v[54:55], v[4:5], 0, v[238:239]
	global_load_lds_dwordx4 v[54:55], off
	v_lshrrev_b32_e32 v2, 4, v0
	v_bfe_u32 v3, v0, 4, 2
	v_and_b32_e32 v4, 7, v0
	v_lshrrev_b32_e32 v5, 2, v0
	v_and_or_b32 v62, v5, 32, v174
	v_bitop3_b32 v2, v2, v4, 3 bitop3:0x6c
	v_bitop3_b32 v3, v3, v4, 4 bitop3:0x36
	v_and_b32_e32 v5, 0x7c00, v6
	v_lshlrev_b32_e32 v4, 4, v4
	v_lshlrev_b32_e32 v64, 4, v2
	v_or3_b32 v2, s4, v5, v4
	s_sub_i32 s4, s11, s17
	s_and_b32 s4, s4, 3
	v_lshlrev_b32_e32 v7, 7, v8
	v_xor_b32_e32 v8, v8, v0
	s_lshl_b32 s4, s4, 17
	s_movk_i32 s6, 0x70
	v_and_b32_e32 v63, 0x2780, v6
	v_lshlrev_b32_e32 v6, 4, v8
	v_lshlrev_b32_e32 v66, 4, v3
	v_mov_b32_e32 v3, s5
	v_or3_b32 v14, s4, v5, v4
	s_mov_b32 s3, 0
	v_lshlrev_b32_e32 v65, 7, v62
	v_and_or_b32 v67, v6, s6, v7
	v_lshl_add_u64 v[58:59], s[26:27], 0, v[2:3]
	v_lshl_add_u64 v[60:61], s[54:55], 0, v[14:15]
	s_mov_b64 s[4:5], 0
	s_mov_b32 s11, 0
	v_mov_b32_e32 v14, v15
	v_mov_b32_e32 v16, v15
	v_mov_b32_e32 v17, v15
	v_mov_b32_e32 v30, v15
	v_mov_b32_e32 v31, v15
	v_mov_b32_e32 v32, v15
	v_mov_b32_e32 v33, v15
	v_mov_b32_e32 v26, v15
	v_mov_b32_e32 v27, v15
	v_mov_b32_e32 v28, v15
	v_mov_b32_e32 v29, v15
	v_mov_b32_e32 v22, v15
	v_mov_b32_e32 v23, v15
	v_mov_b32_e32 v24, v15
	v_mov_b32_e32 v25, v15
	v_mov_b32_e32 v18, v15
	v_mov_b32_e32 v19, v15
	v_mov_b32_e32 v20, v15
	v_mov_b32_e32 v21, v15
	v_mov_b32_e32 v10, v15
	v_mov_b32_e32 v11, v15
	v_mov_b32_e32 v12, v15
	v_mov_b32_e32 v13, v15
	v_mov_b32_e32 v6, v15
	v_mov_b32_e32 v7, v15
	v_mov_b32_e32 v8, v15
	v_mov_b32_e32 v9, v15
	v_mov_b32_e32 v2, v15
	v_mov_b32_e32 v3, v15
	v_mov_b32_e32 v4, v15
	v_mov_b32_e32 v5, v15
	v_readlane_b32 s69, v237, 36
	v_readlane_b32 s70, v237, 37
	v_readlane_b32 s71, v237, 38
	v_readlane_b32 s72, v237, 39
	v_readlane_b32 s73, v237, 40
	v_readlane_b32 s74, v237, 41
	v_readlane_b32 s75, v237, 42
	v_readlane_b32 s76, v237, 43
	v_readlane_b32 s77, v237, 44
	v_readlane_b32 s78, v237, 45
	v_readlane_b32 s79, v237, 46
	s_waitcnt lgkmcnt(0)
	s_waitcnt vmcnt(0)
	s_barrier
	s_branch .LBB0_744
.LBB0_743:
	s_add_u32 s4, s4, 0x80
	s_addc_u32 s5, s5, 0
	s_add_i32 s11, s11, 1
	s_cmpk_lg_i32 s4, 0x400
	s_mov_b32 s3, s6
	s_waitcnt lgkmcnt(0)
	s_waitcnt vmcnt(0)
	s_barrier
	s_cbranch_scc0 .LBB0_750
.LBB0_744:
	s_cmp_gt_u32 s11, 6
	s_cselect_b64 s[6:7], -1, 0
	s_and_b64 vcc, exec, s[6:7]
	s_cbranch_vccnz .LBB0_746
	s_and_b32 s99, s3, 0x8000
	s_xor_b32 s99, s99, 0x8000
	s_add_u32 s99, s99, s98
	s_mov_b32 m0, s99
	v_lshl_add_u64 v[34:35], v[34:35], 0, v[242:243]
	global_load_lds_dwordx4 v[34:35], off
	s_add_u32 m0, s99, 0x1000
	v_lshl_add_u64 v[38:39], v[38:39], 0, v[242:243]
	global_load_lds_dwordx4 v[38:39], off
	s_add_u32 m0, s99, 0x4000
	v_lshl_add_u64 v[42:43], v[42:43], 0, v[242:243]
	global_load_lds_dwordx4 v[42:43], off
	s_add_u32 m0, s99, 0x5000
	v_lshl_add_u64 v[46:47], v[46:47], 0, v[242:243]
	global_load_lds_dwordx4 v[46:47], off
	s_add_u32 m0, s99, 0x6000
	v_lshl_add_u64 v[50:51], v[50:51], 0, v[242:243]
	global_load_lds_dwordx4 v[50:51], off
	s_add_u32 m0, s99, 0x7000
	v_lshl_add_u64 v[54:55], v[54:55], 0, v[242:243]
	global_load_lds_dwordx4 v[54:55], off

.LBB0_748:
	s_andn2_b64 vcc, exec, s[8:9]
	s_cbranch_vccnz .LBB0_743
	s_add_i32 s6, s3, 0x8000
	s_and_b32 s3, s6, 0x8000
	v_or_b32_e32 v68, s3, v67
	s_branch .LBB0_743

.LBB0_820:
	s_lshl_b32 s10, s13, 7
	s_ashr_i32 s11, s10, 31
	s_lshl_b64 s[20:21], s[10:11], 10
	s_waitcnt lgkmcnt(0)
	v_lshl_add_u64 v[2:3], v[98:99], 0, s[20:21]
	v_add_co_u32_e32 v4, vcc, s23, v2
	s_lshl_b32 s12, s12, 7
	s_nop 0
	v_addc_co_u32_e32 v5, vcc, 0, v3, vcc
	v_add_co_u32_e32 v6, vcc, s24, v2
	s_ashr_i32 s13, s12, 31
	s_nop 0
	v_addc_co_u32_e32 v7, vcc, 0, v3, vcc
	s_lshl_b64 s[18:19], s[12:13], 11
	s_barrier
	s_add_u32 m0, s98, 0x1000
	v_lshl_add_u64 v[66:67], v[4:5], 0, v[238:239]
	global_load_lds_dwordx4 v[66:67], off
	s_add_u32 m0, s98, 0x2000
	v_lshl_add_u64 v[74:75], v[6:7], 0, v[238:239]
	global_load_lds_dwordx4 v[74:75], off
	v_add_co_u32_e32 v4, vcc, s25, v2
	v_lshl_add_u64 v[112:113], v[102:103], 0, s[18:19]
	s_nop 0
	v_addc_co_u32_e32 v5, vcc, 0, v3, vcc
	s_mov_b32 m0, s98
	v_lshl_add_u64 v[70:71], v[2:3], 0, v[238:239]
	global_load_lds_dwordx4 v[70:71], off
	s_add_u32 m0, s98, 0x4000
	v_lshl_add_u64 v[82:83], v[112:113], 0, v[238:239]
	global_load_lds_dwordx4 v[82:83], off
	v_add_co_u32_e32 v2, vcc, s24, v112
	v_mov_b32_e32 v46, 0
	s_nop 0
	v_addc_co_u32_e32 v3, vcc, 0, v113, vcc
	s_add_u32 m0, s98, 0x3000
	v_lshl_add_u64 v[78:79], v[4:5], 0, v[238:239]
	global_load_lds_dwordx4 v[78:79], off
	s_add_u32 m0, s98, 0x5000
	v_lshl_add_u64 v[86:87], v[2:3], 0, v[238:239]
	global_load_lds_dwordx4 v[86:87], off
	v_add_co_u32_e32 v2, vcc, s26, v112
	s_mov_b32 s31, 0
	s_nop 0
	v_addc_co_u32_e32 v3, vcc, 0, v113, vcc
	v_add_co_u32_e32 v4, vcc, s27, v112
	s_mov_b64 s[14:15], 0
	s_nop 0
	v_addc_co_u32_e32 v5, vcc, 0, v113, vcc
	s_add_u32 m0, s98, 0x6000
	v_lshl_add_u64 v[90:91], v[2:3], 0, v[238:239]
	global_load_lds_dwordx4 v[90:91], off
	s_add_u32 m0, s98, 0x7000
	v_lshl_add_u64 v[94:95], v[4:5], 0, v[238:239]
	global_load_lds_dwordx4 v[94:95], off
	s_mov_b32 s13, 0
	v_mov_b32_e32 v47, v46
	v_mov_b32_e32 v48, v46
	v_mov_b32_e32 v49, v46
	v_mov_b32_e32 v58, v46
	v_mov_b32_e32 v59, v46
	v_mov_b32_e32 v60, v46
	v_mov_b32_e32 v61, v46
	v_mov_b32_e32 v62, v46
	v_mov_b32_e32 v63, v46
	v_mov_b32_e32 v64, v46
	v_mov_b32_e32 v65, v46
	v_mov_b32_e32 v54, v46
	v_mov_b32_e32 v55, v46
	v_mov_b32_e32 v56, v46
	v_mov_b32_e32 v57, v46
	v_mov_b32_e32 v14, v46
	v_mov_b32_e32 v15, v46
	v_mov_b32_e32 v16, v46
	v_mov_b32_e32 v17, v46
	v_mov_b32_e32 v6, v46
	v_mov_b32_e32 v7, v46
	v_mov_b32_e32 v8, v46
	v_mov_b32_e32 v9, v46
	v_mov_b32_e32 v10, v46
	v_mov_b32_e32 v11, v46
	s_lshl_b64 s[16:17], s[10:11], 9
	v_lshl_add_u64 v[108:109], v[104:105], 0, s[20:21]
	v_lshl_add_u64 v[110:111], v[106:107], 0, s[18:19]
	v_mov_b32_e32 v12, v46
	v_mov_b32_e32 v13, v46
	v_mov_b32_e32 v50, v46
	v_mov_b32_e32 v51, v46
	v_mov_b32_e32 v52, v46
	v_mov_b32_e32 v53, v46
	v_mov_b32_e32 v42, v46
	v_mov_b32_e32 v43, v46
	v_mov_b32_e32 v44, v46
	v_mov_b32_e32 v45, v46
	v_mov_b32_e32 v30, v46
	v_mov_b32_e32 v31, v46
	v_mov_b32_e32 v32, v46
	v_mov_b32_e32 v33, v46
	v_mov_b32_e32 v34, v46
	v_mov_b32_e32 v35, v46
	v_mov_b32_e32 v36, v46
	v_mov_b32_e32 v37, v46
	v_mov_b32_e32 v38, v46
	v_mov_b32_e32 v39, v46
	v_mov_b32_e32 v40, v46
	v_mov_b32_e32 v41, v46
	v_mov_b32_e32 v26, v46
	v_mov_b32_e32 v27, v46
	v_mov_b32_e32 v28, v46
	v_mov_b32_e32 v29, v46
	v_mov_b32_e32 v22, v46
	v_mov_b32_e32 v23, v46
	v_mov_b32_e32 v24, v46
	v_mov_b32_e32 v25, v46
	v_mov_b32_e32 v18, v46
	v_mov_b32_e32 v19, v46
	v_mov_b32_e32 v20, v46
	v_mov_b32_e32 v21, v46
	v_mov_b32_e32 v2, v46
	v_mov_b32_e32 v3, v46
	v_mov_b32_e32 v4, v46
	v_mov_b32_e32 v5, v46
	s_waitcnt lgkmcnt(0)
	s_waitcnt vmcnt(0)
	s_barrier
	s_branch .LBB0_822
.LBB0_821:
	s_add_u32 s14, s14, 0x80
	s_addc_u32 s15, s15, 0
	s_add_i32 s13, s13, 1
	s_cmpk_lg_i32 s14, 0x400
	s_mov_b32 s31, s11
	s_waitcnt lgkmcnt(0)
	s_waitcnt vmcnt(0)
	s_barrier
	s_cbranch_scc0 .LBB0_828
.LBB0_822:
	s_cmp_gt_u32 s13, 6
	s_cselect_b64 s[18:19], -1, 0
	s_and_b64 vcc, exec, s[18:19]
	s_cbranch_vccnz .LBB0_824
	s_and_b32 s99, s31, 0x8000
	s_xor_b32 s99, s99, 0x8000
	s_add_u32 s99, s99, s98
	s_mov_b32 m0, s99
	v_lshl_add_u64 v[70:71], v[70:71], 0, v[242:243]
	global_load_lds_dwordx4 v[70:71], off
	s_add_u32 m0, s99, 0x1000
	v_lshl_add_u64 v[66:67], v[66:67], 0, v[242:243]
	global_load_lds_dwordx4 v[66:67], off
	s_add_u32 m0, s99, 0x2000
	v_lshl_add_u64 v[74:75], v[74:75], 0, v[242:243]
	global_load_lds_dwordx4 v[74:75], off
	s_add_u32 m0, s99, 0x3000
	v_lshl_add_u64 v[78:79], v[78:79], 0, v[242:243]
	global_load_lds_dwordx4 v[78:79], off
	s_add_u32 m0, s99, 0x4000
	v_lshl_add_u64 v[82:83], v[82:83], 0, v[242:243]
	global_load_lds_dwordx4 v[82:83], off
	s_add_u32 m0, s99, 0x5000
	v_lshl_add_u64 v[86:87], v[86:87], 0, v[242:243]
	global_load_lds_dwordx4 v[86:87], off
	s_add_u32 m0, s99, 0x6000
	v_lshl_add_u64 v[90:91], v[90:91], 0, v[242:243]
	global_load_lds_dwordx4 v[90:91], off
	s_add_u32 m0, s99, 0x7000
	v_lshl_add_u64 v[94:95], v[94:95], 0, v[242:243]
	global_load_lds_dwordx4 v[94:95], off

.LBB0_826:
	s_andn2_b64 vcc, exec, s[20:21]
	s_cbranch_vccnz .LBB0_821
	s_add_i32 s11, s31, 0x8000
	s_and_b32 s18, s11, 0x8000
	v_or_b32_e32 v124, s18, v114
	s_branch .LBB0_821
.LBB0_828:
	s_waitcnt vmcnt(7)
	v_lshl_add_u64 v[70:71], s[16:17], 1, v[100:101]
	s_waitcnt vmcnt(6)
	v_add_co_u32_e32 v66, vcc, 0x8000, v70
	s_nop 1
	v_addc_co_u32_e32 v67, vcc, 0, v71, vcc
	v_add_co_u32_e32 v72, vcc, 0x10000, v70
	s_barrier
	s_nop 0
	v_addc_co_u32_e32 v73, vcc, 0, v71, vcc
	s_waitcnt vmcnt(4)
	v_add_co_u32_e32 v78, vcc, 0x18000, v70
	s_nop 1
	v_addc_co_u32_e32 v79, vcc, 0, v71, vcc
	s_waitcnt vmcnt(2)
	v_add_co_u32_e32 v86, vcc, 0x10000, v112
	s_add_u32 m0, s98, 0x1000
	v_lshl_add_u64 v[66:67], v[66:67], 0, v[238:239]
	global_load_lds_dwordx4 v[66:67], off
	s_nop 0
	s_add_u32 m0, s98, 0x2000
	v_lshl_add_u64 v[74:75], v[72:73], 0, v[238:239]
	global_load_lds_dwordx4 v[74:75], off
	v_addc_co_u32_e32 v87, vcc, 0, v113, vcc
	v_add_co_u32_e32 v90, vcc, 0x20000, v112
	s_mov_b32 m0, s98
	v_lshl_add_u64 v[70:71], v[70:71], 0, v[238:239]
	global_load_lds_dwordx4 v[70:71], off
	s_nop 0
	s_add_u32 m0, s98, 0x4000
	v_lshl_add_u64 v[82:83], v[112:113], 0, v[240:241]
	global_load_lds_dwordx4 v[82:83], off
	v_addc_co_u32_e32 v91, vcc, 0, v113, vcc
	v_add_co_u32_e32 v94, vcc, 0x30000, v112
	s_add_u32 m0, s98, 0x3000
	v_lshl_add_u64 v[78:79], v[78:79], 0, v[238:239]
	global_load_lds_dwordx4 v[78:79], off
	s_nop 0
	s_add_u32 m0, s98, 0x5000
	v_lshl_add_u64 v[86:87], v[86:87], 0, v[240:241]
	global_load_lds_dwordx4 v[86:87], off
	v_addc_co_u32_e32 v95, vcc, 0, v113, vcc
	s_add_u32 m0, s98, 0x6000
	v_lshl_add_u64 v[90:91], v[90:91], 0, v[240:241]
	global_load_lds_dwordx4 v[90:91], off
	s_nop 0
	s_add_u32 m0, s98, 0x7000
	v_lshl_add_u64 v[94:95], v[94:95], 0, v[240:241]
	global_load_lds_dwordx4 v[94:95], off
	s_mov_b32 s11, 0
	s_mov_b64 s[14:15], 0
	s_mov_b32 s13, 0
	s_waitcnt lgkmcnt(0)
	s_waitcnt vmcnt(0)
	s_barrier
	s_branch .LBB0_830
.LBB0_829:
	s_add_u32 s14, s14, 0x80
	s_addc_u32 s15, s15, 0
	s_add_i32 s13, s13, 1
	s_cmpk_lg_i32 s14, 0x400
	s_mov_b32 s11, s16
	s_waitcnt lgkmcnt(0)
	s_waitcnt vmcnt(0)
	s_barrier
	s_cbranch_scc0 .LBB0_836
.LBB0_830:
	s_cmp_gt_u32 s13, 6
	s_cselect_b64 s[16:17], -1, 0
	s_and_b64 vcc, exec, s[16:17]
	s_cbranch_vccnz .LBB0_832
	s_and_b32 s99, s11, 0x8000
	s_xor_b32 s99, s99, 0x8000
	s_add_u32 s99, s99, s98
	s_mov_b32 m0, s99
	v_lshl_add_u64 v[70:71], v[70:71], 0, v[242:243]
	global_load_lds_dwordx4 v[70:71], off
	s_add_u32 m0, s99, 0x1000
	v_lshl_add_u64 v[66:67], v[66:67], 0, v[242:243]
	global_load_lds_dwordx4 v[66:67], off
	s_add_u32 m0, s99, 0x2000
	v_lshl_add_u64 v[74:75], v[74:75], 0, v[242:243]
	global_load_lds_dwordx4 v[74:75], off
	s_add_u32 m0, s99, 0x3000
	v_lshl_add_u64 v[78:79], v[78:79], 0, v[242:243]
	global_load_lds_dwordx4 v[78:79], off
	s_add_u32 m0, s99, 0x4000
	v_lshl_add_u64 v[82:83], v[82:83], 0, v[242:243]
	global_load_lds_dwordx4 v[82:83], off
	s_add_u32 m0, s99, 0x5000
	v_lshl_add_u64 v[86:87], v[86:87], 0, v[242:243]
	global_load_lds_dwordx4 v[86:87], off
	s_add_u32 m0, s99, 0x6000
	v_lshl_add_u64 v[90:91], v[90:91], 0, v[242:243]
	global_load_lds_dwordx4 v[90:91], off
	s_add_u32 m0, s99, 0x7000
	v_lshl_add_u64 v[94:95], v[94:95], 0, v[242:243]
	global_load_lds_dwordx4 v[94:95], off

.LBB0_834:
	s_andn2_b64 vcc, exec, s[18:19]
	s_cbranch_vccnz .LBB0_829
	s_add_i32 s16, s11, 0x8000
	s_and_b32 s11, s16, 0x8000
	v_or_b32_e32 v112, s11, v114
	s_branch .LBB0_829

.LBB0_853:
	s_lshl_b32 s8, s11, 7
	s_ashr_i32 s9, s8, 31
	s_lshl_b64 s[18:19], s[8:9], 10
	s_waitcnt lgkmcnt(0)
	v_lshl_add_u64 v[2:3], v[98:99], 0, s[18:19]
	v_add_co_u32_e32 v4, vcc, s23, v2
	s_lshl_b32 s10, s10, 7
	s_nop 0
	v_addc_co_u32_e32 v5, vcc, 0, v3, vcc
	v_add_co_u32_e32 v6, vcc, s24, v2
	s_ashr_i32 s11, s10, 31
	s_nop 0
	v_addc_co_u32_e32 v7, vcc, 0, v3, vcc
	s_lshl_b64 s[16:17], s[10:11], 11
	s_barrier
	s_add_u32 m0, s98, 0x1000
	v_lshl_add_u64 v[66:67], v[4:5], 0, v[238:239]
	global_load_lds_dwordx4 v[66:67], off
	s_add_u32 m0, s98, 0x2000
	v_lshl_add_u64 v[74:75], v[6:7], 0, v[238:239]
	global_load_lds_dwordx4 v[74:75], off
	v_add_co_u32_e32 v4, vcc, s25, v2
	v_lshl_add_u64 v[112:113], v[102:103], 0, s[16:17]
	s_nop 0
	v_addc_co_u32_e32 v5, vcc, 0, v3, vcc
	s_mov_b32 m0, s98
	v_lshl_add_u64 v[70:71], v[2:3], 0, v[238:239]
	global_load_lds_dwordx4 v[70:71], off
	s_add_u32 m0, s98, 0x4000
	v_lshl_add_u64 v[82:83], v[112:113], 0, v[238:239]
	global_load_lds_dwordx4 v[82:83], off
	v_add_co_u32_e32 v2, vcc, s24, v112
	v_mov_b32_e32 v46, 0
	s_nop 0
	v_addc_co_u32_e32 v3, vcc, 0, v113, vcc
	s_add_u32 m0, s98, 0x3000
	v_lshl_add_u64 v[78:79], v[4:5], 0, v[238:239]
	global_load_lds_dwordx4 v[78:79], off
	s_add_u32 m0, s98, 0x5000
	v_lshl_add_u64 v[86:87], v[2:3], 0, v[238:239]
	global_load_lds_dwordx4 v[86:87], off
	v_add_co_u32_e32 v2, vcc, s26, v112
	s_mov_b32 s31, 0
	s_nop 0
	v_addc_co_u32_e32 v3, vcc, 0, v113, vcc
	v_add_co_u32_e32 v4, vcc, s27, v112
	s_mov_b64 s[12:13], 0
	s_nop 0
	v_addc_co_u32_e32 v5, vcc, 0, v113, vcc
	s_add_u32 m0, s98, 0x6000
	v_lshl_add_u64 v[90:91], v[2:3], 0, v[238:239]
	global_load_lds_dwordx4 v[90:91], off
	s_add_u32 m0, s98, 0x7000
	v_lshl_add_u64 v[94:95], v[4:5], 0, v[238:239]
	global_load_lds_dwordx4 v[94:95], off
	s_mov_b32 s11, 0
	v_mov_b32_e32 v47, v46
	v_mov_b32_e32 v48, v46
	v_mov_b32_e32 v49, v46
	v_mov_b32_e32 v58, v46
	v_mov_b32_e32 v59, v46
	v_mov_b32_e32 v60, v46
	v_mov_b32_e32 v61, v46
	v_mov_b32_e32 v62, v46
	v_mov_b32_e32 v63, v46
	v_mov_b32_e32 v64, v46
	v_mov_b32_e32 v65, v46
	v_mov_b32_e32 v54, v46
	v_mov_b32_e32 v55, v46
	v_mov_b32_e32 v56, v46
	v_mov_b32_e32 v57, v46
	v_mov_b32_e32 v14, v46
	v_mov_b32_e32 v15, v46
	v_mov_b32_e32 v16, v46
	v_mov_b32_e32 v17, v46
	v_mov_b32_e32 v6, v46
	v_mov_b32_e32 v7, v46
	v_mov_b32_e32 v8, v46
	v_mov_b32_e32 v9, v46
	v_mov_b32_e32 v10, v46
	v_mov_b32_e32 v11, v46
	s_lshl_b64 s[14:15], s[8:9], 9
	v_lshl_add_u64 v[108:109], v[104:105], 0, s[18:19]
	v_lshl_add_u64 v[110:111], v[106:107], 0, s[16:17]
	v_mov_b32_e32 v12, v46
	v_mov_b32_e32 v13, v46
	v_mov_b32_e32 v50, v46
	v_mov_b32_e32 v51, v46
	v_mov_b32_e32 v52, v46
	v_mov_b32_e32 v53, v46
	v_mov_b32_e32 v42, v46
	v_mov_b32_e32 v43, v46
	v_mov_b32_e32 v44, v46
	v_mov_b32_e32 v45, v46
	v_mov_b32_e32 v30, v46
	v_mov_b32_e32 v31, v46
	v_mov_b32_e32 v32, v46
	v_mov_b32_e32 v33, v46
	v_mov_b32_e32 v34, v46
	v_mov_b32_e32 v35, v46
	v_mov_b32_e32 v36, v46
	v_mov_b32_e32 v37, v46
	v_mov_b32_e32 v38, v46
	v_mov_b32_e32 v39, v46
	v_mov_b32_e32 v40, v46
	v_mov_b32_e32 v41, v46
	v_mov_b32_e32 v26, v46
	v_mov_b32_e32 v27, v46
	v_mov_b32_e32 v28, v46
	v_mov_b32_e32 v29, v46
	v_mov_b32_e32 v22, v46
	v_mov_b32_e32 v23, v46
	v_mov_b32_e32 v24, v46
	v_mov_b32_e32 v25, v46
	v_mov_b32_e32 v18, v46
	v_mov_b32_e32 v19, v46
	v_mov_b32_e32 v20, v46
	v_mov_b32_e32 v21, v46
	v_mov_b32_e32 v2, v46
	v_mov_b32_e32 v3, v46
	v_mov_b32_e32 v4, v46
	v_mov_b32_e32 v5, v46
	s_waitcnt lgkmcnt(0)
	s_waitcnt vmcnt(0)
	s_barrier
	s_branch .LBB0_855
.LBB0_854:
	s_add_u32 s12, s12, 0x80
	s_addc_u32 s13, s13, 0
	s_add_i32 s11, s11, 1
	s_cmpk_lg_i32 s12, 0x400
	s_mov_b32 s31, s9
	s_waitcnt lgkmcnt(0)
	s_waitcnt vmcnt(0)
	s_barrier
	s_cbranch_scc0 .LBB0_861
.LBB0_855:
	s_cmp_gt_u32 s11, 6
	s_cselect_b64 s[16:17], -1, 0
	s_and_b64 vcc, exec, s[16:17]
	s_cbranch_vccnz .LBB0_857
	s_and_b32 s99, s31, 0x8000
	s_xor_b32 s99, s99, 0x8000
	s_add_u32 s99, s99, s98
	s_mov_b32 m0, s99
	v_lshl_add_u64 v[70:71], v[70:71], 0, v[242:243]
	global_load_lds_dwordx4 v[70:71], off
	s_add_u32 m0, s99, 0x1000
	v_lshl_add_u64 v[66:67], v[66:67], 0, v[242:243]
	global_load_lds_dwordx4 v[66:67], off
	s_add_u32 m0, s99, 0x2000
	v_lshl_add_u64 v[74:75], v[74:75], 0, v[242:243]
	global_load_lds_dwordx4 v[74:75], off
	s_add_u32 m0, s99, 0x3000
	v_lshl_add_u64 v[78:79], v[78:79], 0, v[242:243]
	global_load_lds_dwordx4 v[78:79], off
	s_add_u32 m0, s99, 0x4000
	v_lshl_add_u64 v[82:83], v[82:83], 0, v[242:243]
	global_load_lds_dwordx4 v[82:83], off
	s_add_u32 m0, s99, 0x5000
	v_lshl_add_u64 v[86:87], v[86:87], 0, v[242:243]
	global_load_lds_dwordx4 v[86:87], off
	s_add_u32 m0, s99, 0x6000
	v_lshl_add_u64 v[90:91], v[90:91], 0, v[242:243]
	global_load_lds_dwordx4 v[90:91], off
	s_add_u32 m0, s99, 0x7000
	v_lshl_add_u64 v[94:95], v[94:95], 0, v[242:243]
	global_load_lds_dwordx4 v[94:95], off

.LBB0_859:
	s_andn2_b64 vcc, exec, s[18:19]
	s_cbranch_vccnz .LBB0_854
	s_add_i32 s9, s31, 0x8000
	s_and_b32 s16, s9, 0x8000
	v_or_b32_e32 v124, s16, v114
	s_branch .LBB0_854
.LBB0_861:
	s_waitcnt vmcnt(7)
	v_lshl_add_u64 v[70:71], s[14:15], 1, v[100:101]
	s_waitcnt vmcnt(6)
	v_add_co_u32_e32 v66, vcc, 0x8000, v70
	s_nop 1
	v_addc_co_u32_e32 v67, vcc, 0, v71, vcc
	v_add_co_u32_e32 v72, vcc, 0x10000, v70
	s_barrier
	s_nop 0
	v_addc_co_u32_e32 v73, vcc, 0, v71, vcc
	s_waitcnt vmcnt(4)
	v_add_co_u32_e32 v78, vcc, 0x18000, v70
	s_nop 1
	v_addc_co_u32_e32 v79, vcc, 0, v71, vcc
	s_waitcnt vmcnt(2)
	v_add_co_u32_e32 v86, vcc, 0x10000, v112
	s_add_u32 m0, s98, 0x1000
	v_lshl_add_u64 v[66:67], v[66:67], 0, v[238:239]
	global_load_lds_dwordx4 v[66:67], off
	s_nop 0
	s_add_u32 m0, s98, 0x2000
	v_lshl_add_u64 v[74:75], v[72:73], 0, v[238:239]
	global_load_lds_dwordx4 v[74:75], off
	v_addc_co_u32_e32 v87, vcc, 0, v113, vcc
	v_add_co_u32_e32 v90, vcc, 0x20000, v112
	s_mov_b32 m0, s98
	v_lshl_add_u64 v[70:71], v[70:71], 0, v[238:239]
	global_load_lds_dwordx4 v[70:71], off
	s_nop 0
	s_add_u32 m0, s98, 0x4000
	v_lshl_add_u64 v[82:83], v[112:113], 0, v[240:241]
	global_load_lds_dwordx4 v[82:83], off
	v_addc_co_u32_e32 v91, vcc, 0, v113, vcc
	v_add_co_u32_e32 v94, vcc, 0x30000, v112
	s_add_u32 m0, s98, 0x3000
	v_lshl_add_u64 v[78:79], v[78:79], 0, v[238:239]
	global_load_lds_dwordx4 v[78:79], off
	s_nop 0
	s_add_u32 m0, s98, 0x5000
	v_lshl_add_u64 v[86:87], v[86:87], 0, v[240:241]
	global_load_lds_dwordx4 v[86:87], off
	v_addc_co_u32_e32 v95, vcc, 0, v113, vcc
	s_add_u32 m0, s98, 0x6000
	v_lshl_add_u64 v[90:91], v[90:91], 0, v[240:241]
	global_load_lds_dwordx4 v[90:91], off
	s_nop 0
	s_add_u32 m0, s98, 0x7000
	v_lshl_add_u64 v[94:95], v[94:95], 0, v[240:241]
	global_load_lds_dwordx4 v[94:95], off
	s_mov_b32 s9, 0
	s_mov_b64 s[12:13], 0
	s_mov_b32 s11, 0
	s_waitcnt lgkmcnt(0)
	s_waitcnt vmcnt(0)
	s_barrier
	s_branch .LBB0_863
.LBB0_862:
	s_add_u32 s12, s12, 0x80
	s_addc_u32 s13, s13, 0
	s_add_i32 s11, s11, 1
	s_cmpk_lg_i32 s12, 0x400
	s_mov_b32 s9, s14
	s_waitcnt lgkmcnt(0)
	s_waitcnt vmcnt(0)
	s_barrier
	s_cbranch_scc0 .LBB0_869
.LBB0_863:
	s_cmp_gt_u32 s11, 6
	s_cselect_b64 s[14:15], -1, 0
	s_and_b64 vcc, exec, s[14:15]
	s_cbranch_vccnz .LBB0_865
	s_and_b32 s99, s9, 0x8000
	s_xor_b32 s99, s99, 0x8000
	s_add_u32 s99, s99, s98
	s_mov_b32 m0, s99
	v_lshl_add_u64 v[70:71], v[70:71], 0, v[242:243]
	global_load_lds_dwordx4 v[70:71], off
	s_add_u32 m0, s99, 0x1000
	v_lshl_add_u64 v[66:67], v[66:67], 0, v[242:243]
	global_load_lds_dwordx4 v[66:67], off
	s_add_u32 m0, s99, 0x2000
	v_lshl_add_u64 v[74:75], v[74:75], 0, v[242:243]
	global_load_lds_dwordx4 v[74:75], off
	s_add_u32 m0, s99, 0x3000
	v_lshl_add_u64 v[78:79], v[78:79], 0, v[242:243]
	global_load_lds_dwordx4 v[78:79], off
	s_add_u32 m0, s99, 0x4000
	v_lshl_add_u64 v[82:83], v[82:83], 0, v[242:243]
	global_load_lds_dwordx4 v[82:83], off
	s_add_u32 m0, s99, 0x5000
	v_lshl_add_u64 v[86:87], v[86:87], 0, v[242:243]
	global_load_lds_dwordx4 v[86:87], off
	s_add_u32 m0, s99, 0x6000
	v_lshl_add_u64 v[90:91], v[90:91], 0, v[242:243]
	global_load_lds_dwordx4 v[90:91], off
	s_add_u32 m0, s99, 0x7000
	v_lshl_add_u64 v[94:95], v[94:95], 0, v[242:243]
	global_load_lds_dwordx4 v[94:95], off

.LBB0_867:
	s_andn2_b64 vcc, exec, s[16:17]
	s_cbranch_vccnz .LBB0_862
	s_add_i32 s14, s9, 0x8000
	s_and_b32 s9, s14, 0x8000
	v_or_b32_e32 v112, s9, v114
	s_branch .LBB0_862

.LBB0_884:
	s_lshl_b32 s5, s59, 6
	s_lshl_b32 s4, s12, 7
	s_and_b32 s5, s5, 64
	s_or_b32 s4, s4, s5
	s_ashr_i32 s5, s4, 31
	s_lshl_b32 s10, s11, 7
	s_lshl_b64 s[12:13], s[4:5], 9
	s_lshl_b64 s[14:15], s[4:5], 10
	s_add_u32 s18, s54, s14
	s_addc_u32 s19, s55, s15
	s_ashr_i32 s11, s10, 31
	s_lshl_b64 s[16:17], s[10:11], 11
	v_lshrrev_b32_e32 v12, 3, v0
	v_lshlrev_b32_e32 v6, 3, v0
	s_add_u32 s24, s54, s16
	s_waitcnt lgkmcnt(0)
	v_mov_b32_e32 v3, 0
	v_lshlrev_b32_e32 v2, 10, v12
	s_waitcnt vmcnt(51)
	v_and_b32_e32 v62, 56, v6
	s_addc_u32 s25, s55, s17
	v_lshl_add_u64 v[4:5], s[18:19], 0, v[2:3]
	v_lshlrev_b32_e32 v6, 1, v62
	v_mov_b32_e32 v7, v3
	v_lshlrev_b32_e32 v8, 11, v12
	v_mov_b32_e32 v9, v3
	v_lshl_add_u64 v[4:5], v[4:5], 0, v[6:7]
	v_lshl_add_u64 v[10:11], s[24:25], 0, v[8:9]
	s_mov_b32 s5, 0xd580000
	v_lshl_add_u64 v[6:7], v[10:11], 0, v[6:7]
	v_add_co_u32_e32 v10, vcc, s5, v4
	s_mov_b32 s5, 0xd588000
	s_nop 0
	v_addc_co_u32_e32 v11, vcc, 0, v5, vcc
	v_add_co_u32_e32 v4, vcc, s5, v4
	s_mov_b32 s5, 0xee00000
	s_nop 0
	v_addc_co_u32_e32 v5, vcc, 0, v5, vcc
	s_barrier
	s_mov_b32 m0, s98
	v_lshl_add_u64 v[34:35], v[10:11], 0, v[238:239]
	global_load_lds_dwordx4 v[34:35], off
	s_add_u32 m0, s98, 0x1000
	v_lshl_add_u64 v[38:39], v[4:5], 0, v[238:239]
	global_load_lds_dwordx4 v[38:39], off
	v_add_co_u32_e32 v4, vcc, s5, v6
	s_mov_b32 s5, 0xee10000
	s_nop 0
	v_addc_co_u32_e32 v5, vcc, 0, v7, vcc
	v_add_co_u32_e32 v10, vcc, s5, v6
	s_mov_b32 s5, 0xee20000
	s_nop 0
	v_addc_co_u32_e32 v11, vcc, 0, v7, vcc
	s_add_u32 m0, s98, 0x4000
	v_lshl_add_u64 v[42:43], v[4:5], 0, v[238:239]
	global_load_lds_dwordx4 v[42:43], off
	s_add_u32 m0, s98, 0x5000
	v_lshl_add_u64 v[46:47], v[10:11], 0, v[238:239]
	global_load_lds_dwordx4 v[46:47], off
	v_add_co_u32_e32 v4, vcc, s5, v6
	s_mov_b32 s5, 0xee30000
	s_nop 0
	v_addc_co_u32_e32 v5, vcc, 0, v7, vcc
	v_add_co_u32_e32 v10, vcc, s5, v6
	v_and_b32_e32 v9, 7, v0
	s_nop 0
	v_addc_co_u32_e32 v11, vcc, 0, v7, vcc
	s_add_u32 m0, s98, 0x6000
	v_lshl_add_u64 v[50:51], v[4:5], 0, v[238:239]
	global_load_lds_dwordx4 v[50:51], off
	s_add_u32 m0, s98, 0x7000
	v_lshl_add_u64 v[54:55], v[10:11], 0, v[238:239]
	global_load_lds_dwordx4 v[54:55], off
	v_lshrrev_b32_e32 v4, 4, v0
	v_bitop3_b32 v4, v4, v9, 3 bitop3:0x6c
	v_bfe_u32 v5, v0, 4, 2
	s_mov_b64 s[18:19], 0xee00000
	v_lshlrev_b32_e32 v68, 4, v4
	v_lshlrev_b32_e32 v4, 7, v0
	v_lshrrev_b32_e32 v10, 2, v0
	v_lshl_add_u64 v[64:65], v[6:7], 0, s[18:19]
	v_and_b32_e32 v71, 0x2780, v4
	v_bitop3_b32 v4, v5, v9, 4 bitop3:0x36
	v_lshlrev_b32_e32 v6, 4, v9
	v_lshlrev_b32_e32 v66, 9, v12
	v_lshlrev_b32_e32 v11, 7, v12
	v_xor_b32_e32 v12, v12, v0
	v_and_b32_e32 v63, 32, v10
	v_lshlrev_b32_e32 v72, 4, v4
	v_or3_b32 v4, s14, v2, v6
	v_mov_b32_e32 v5, s15
	s_movk_i32 s11, 0x70
	v_lshlrev_b32_e32 v10, 4, v12
	v_and_or_b32 v67, v0, 15, v63
	v_lshl_add_u64 v[58:59], s[54:55], 0, v[4:5]
	v_or3_b32 v4, s16, v8, v6
	v_mov_b32_e32 v5, s17
	s_mov_b32 s5, 0
	v_and_or_b32 v69, v10, s11, v11
	v_lshlrev_b32_e32 v70, 7, v67
	v_lshl_add_u64 v[60:61], s[54:55], 0, v[4:5]
	s_mov_b64 s[14:15], 0
	s_mov_b32 s11, 0
	v_mov_b32_e32 v2, v3
	v_mov_b32_e32 v4, v3
	v_mov_b32_e32 v5, v3
	v_mov_b32_e32 v22, v3
	v_mov_b32_e32 v23, v3
	v_mov_b32_e32 v24, v3
	v_mov_b32_e32 v25, v3
	v_mov_b32_e32 v26, v3
	v_mov_b32_e32 v27, v3
	v_mov_b32_e32 v28, v3
	v_mov_b32_e32 v29, v3
	v_mov_b32_e32 v30, v3
	v_mov_b32_e32 v31, v3
	v_mov_b32_e32 v32, v3
	v_mov_b32_e32 v33, v3
	v_mov_b32_e32 v14, v3
	v_mov_b32_e32 v15, v3
	v_mov_b32_e32 v16, v3
	v_mov_b32_e32 v17, v3
	v_mov_b32_e32 v18, v3
	v_mov_b32_e32 v19, v3
	v_mov_b32_e32 v20, v3
	v_mov_b32_e32 v21, v3
	v_mov_b32_e32 v10, v3
	v_mov_b32_e32 v11, v3
	v_mov_b32_e32 v12, v3
	v_mov_b32_e32 v13, v3
	v_mov_b32_e32 v6, v3
	v_mov_b32_e32 v7, v3
	v_mov_b32_e32 v8, v3
	v_mov_b32_e32 v9, v3
	s_waitcnt lgkmcnt(0)
	s_waitcnt vmcnt(0)
	s_barrier
	s_branch .LBB0_886
.LBB0_885:
	s_add_u32 s14, s14, 0x80
	s_addc_u32 s15, s15, 0
	s_add_i32 s11, s11, 1
	s_cmpk_lg_i32 s14, 0x400
	s_mov_b32 s5, s16
	s_waitcnt lgkmcnt(0)
	s_waitcnt vmcnt(0)
	s_barrier
	s_cbranch_scc0 .LBB0_892
.LBB0_886:
	s_cmp_gt_u32 s11, 6
	s_cselect_b64 s[16:17], -1, 0
	s_and_b64 vcc, exec, s[16:17]
	s_cbranch_vccnz .LBB0_888
	s_and_b32 s99, s5, 0x8000
	s_xor_b32 s99, s99, 0x8000
	s_add_u32 s99, s99, s98
	s_mov_b32 m0, s99
	v_lshl_add_u64 v[34:35], v[34:35], 0, v[242:243]
	global_load_lds_dwordx4 v[34:35], off
	s_add_u32 m0, s99, 0x1000
	v_lshl_add_u64 v[38:39], v[38:39], 0, v[242:243]
	global_load_lds_dwordx4 v[38:39], off
	s_add_u32 m0, s99, 0x4000
	v_lshl_add_u64 v[42:43], v[42:43], 0, v[242:243]
	global_load_lds_dwordx4 v[42:43], off
	s_add_u32 m0, s99, 0x5000
	v_lshl_add_u64 v[46:47], v[46:47], 0, v[242:243]
	global_load_lds_dwordx4 v[46:47], off
	s_add_u32 m0, s99, 0x6000
	v_lshl_add_u64 v[50:51], v[50:51], 0, v[242:243]
	global_load_lds_dwordx4 v[50:51], off
	s_add_u32 m0, s99, 0x7000
	v_lshl_add_u64 v[54:55], v[54:55], 0, v[242:243]
	global_load_lds_dwordx4 v[54:55], off

.LBB0_890:
	s_andn2_b64 vcc, exec, s[18:19]
	s_cbranch_vccnz .LBB0_885
	s_add_i32 s16, s5, 0x8000
	s_and_b32 s5, s16, 0x8000
	v_or_b32_e32 v73, s5, v69
	s_branch .LBB0_885
.LBB0_892:
	s_lshl_b64 s[12:13], s[12:13], 1
	s_add_u32 s12, s6, s12
	s_addc_u32 s13, s7, s13
	s_waitcnt vmcnt(5)
	v_lshlrev_b32_e32 v34, 1, v66
	v_mov_b32_e32 v35, 0
	v_lshl_add_u64 v[36:37], s[12:13], 0, v[34:35]
	v_lshlrev_b32_e32 v34, 1, v62
	s_waitcnt vmcnt(4)
	v_lshl_add_u64 v[38:39], v[36:37], 0, v[34:35]
	s_waitcnt vmcnt(1)
	v_add_co_u32_e32 v50, vcc, 0x8000, v38
	s_nop 1
	v_addc_co_u32_e32 v51, vcc, 0, v39, vcc
	v_add_co_u32_e32 v52, vcc, 0x10000, v64
	s_barrier
	s_nop 0
	v_addc_co_u32_e32 v53, vcc, 0, v65, vcc
	v_add_co_u32_e32 v74, vcc, 0x20000, v64
	s_nop 1
	v_addc_co_u32_e32 v75, vcc, 0, v65, vcc
	s_mov_b32 m0, s98
	v_lshl_add_u64 v[34:35], v[38:39], 0, v[238:239]
	global_load_lds_dwordx4 v[34:35], off
	s_add_u32 m0, s98, 0x4000
	v_lshl_add_u64 v[42:43], v[64:65], 0, v[240:241]
	global_load_lds_dwordx4 v[42:43], off
	v_add_co_u32_e32 v64, vcc, 0x30000, v64
	s_add_u32 m0, s98, 0x1000
	v_lshl_add_u64 v[38:39], v[50:51], 0, v[238:239]
	global_load_lds_dwordx4 v[38:39], off
	s_add_u32 m0, s98, 0x5000
	v_lshl_add_u64 v[46:47], v[52:53], 0, v[240:241]
	global_load_lds_dwordx4 v[46:47], off
	v_addc_co_u32_e32 v65, vcc, 0, v65, vcc
	s_add_u32 m0, s98, 0x6000
	v_lshl_add_u64 v[50:51], v[74:75], 0, v[240:241]
	global_load_lds_dwordx4 v[50:51], off
	s_add_u32 m0, s98, 0x7000
	v_lshl_add_u64 v[54:55], v[64:65], 0, v[240:241]
	global_load_lds_dwordx4 v[54:55], off
	s_mov_b32 s5, 0
	s_mov_b64 s[12:13], 0
	s_mov_b32 s11, 0
	s_waitcnt lgkmcnt(0)
	s_waitcnt vmcnt(0)
	s_barrier
	s_branch .LBB0_894
.LBB0_893:
	s_add_u32 s12, s12, 0x80
	s_addc_u32 s13, s13, 0
	s_add_i32 s11, s11, 1
	s_cmpk_lg_i32 s12, 0x400
	s_mov_b32 s5, s14
	s_waitcnt lgkmcnt(0)
	s_waitcnt vmcnt(0)
	s_barrier
	s_cbranch_scc0 .LBB0_900
.LBB0_894:
	s_cmp_gt_u32 s11, 6
	s_cselect_b64 s[14:15], -1, 0
	s_and_b64 vcc, exec, s[14:15]
	s_cbranch_vccnz .LBB0_896
	s_and_b32 s99, s5, 0x8000
	s_xor_b32 s99, s99, 0x8000
	s_add_u32 s99, s99, s98
	s_mov_b32 m0, s99
	v_lshl_add_u64 v[34:35], v[34:35], 0, v[242:243]
	global_load_lds_dwordx4 v[34:35], off
	s_add_u32 m0, s99, 0x1000
	v_lshl_add_u64 v[38:39], v[38:39], 0, v[242:243]
	global_load_lds_dwordx4 v[38:39], off
	s_add_u32 m0, s99, 0x4000
	v_lshl_add_u64 v[42:43], v[42:43], 0, v[242:243]
	global_load_lds_dwordx4 v[42:43], off
	s_add_u32 m0, s99, 0x5000
	v_lshl_add_u64 v[46:47], v[46:47], 0, v[242:243]
	global_load_lds_dwordx4 v[46:47], off
	s_add_u32 m0, s99, 0x6000
	v_lshl_add_u64 v[50:51], v[50:51], 0, v[242:243]
	global_load_lds_dwordx4 v[50:51], off
	s_add_u32 m0, s99, 0x7000
	v_lshl_add_u64 v[54:55], v[54:55], 0, v[242:243]
	global_load_lds_dwordx4 v[54:55], off

.LBB0_898:
	s_andn2_b64 vcc, exec, s[16:17]
	s_cbranch_vccnz .LBB0_893
	s_add_i32 s14, s5, 0x8000
	s_and_b32 s5, s14, 0x8000
	v_or_b32_e32 v62, s5, v69
	s_branch .LBB0_893

.LBB0_913:
	s_lshl_b32 s6, s9, 7
	s_ashr_i32 s7, s6, 31
	s_lshl_b64 s[16:17], s[6:7], 10
	s_waitcnt lgkmcnt(0)
	v_lshl_add_u64 v[2:3], v[98:99], 0, s[16:17]
	v_add_co_u32_e32 v4, vcc, s20, v2
	s_lshl_b32 s8, s8, 7
	s_nop 0
	v_addc_co_u32_e32 v5, vcc, 0, v3, vcc
	v_add_co_u32_e32 v6, vcc, s21, v2
	s_ashr_i32 s9, s8, 31
	s_nop 0
	v_addc_co_u32_e32 v7, vcc, 0, v3, vcc
	s_lshl_b64 s[14:15], s[8:9], 11
	s_barrier
	s_add_u32 m0, s98, 0x1000
	v_lshl_add_u64 v[66:67], v[4:5], 0, v[238:239]
	global_load_lds_dwordx4 v[66:67], off
	s_add_u32 m0, s98, 0x2000
	v_lshl_add_u64 v[74:75], v[6:7], 0, v[238:239]
	global_load_lds_dwordx4 v[74:75], off
	v_add_co_u32_e32 v4, vcc, s22, v2
	v_lshl_add_u64 v[112:113], v[102:103], 0, s[14:15]
	s_nop 0
	v_addc_co_u32_e32 v5, vcc, 0, v3, vcc
	s_mov_b32 m0, s98
	v_lshl_add_u64 v[70:71], v[2:3], 0, v[238:239]
	global_load_lds_dwordx4 v[70:71], off
	s_add_u32 m0, s98, 0x4000
	v_lshl_add_u64 v[82:83], v[112:113], 0, v[238:239]
	global_load_lds_dwordx4 v[82:83], off
	v_add_co_u32_e32 v2, vcc, s21, v112
	v_mov_b32_e32 v46, 0
	s_nop 0
	v_addc_co_u32_e32 v3, vcc, 0, v113, vcc
	s_add_u32 m0, s98, 0x3000
	v_lshl_add_u64 v[78:79], v[4:5], 0, v[238:239]
	global_load_lds_dwordx4 v[78:79], off
	s_add_u32 m0, s98, 0x5000
	v_lshl_add_u64 v[86:87], v[2:3], 0, v[238:239]
	global_load_lds_dwordx4 v[86:87], off
	v_add_co_u32_e32 v2, vcc, s23, v112
	s_mov_b32 s27, 0
	s_nop 0
	v_addc_co_u32_e32 v3, vcc, 0, v113, vcc
	v_add_co_u32_e32 v4, vcc, s24, v112
	s_mov_b64 s[10:11], 0
	s_nop 0
	v_addc_co_u32_e32 v5, vcc, 0, v113, vcc
	s_add_u32 m0, s98, 0x6000
	v_lshl_add_u64 v[90:91], v[2:3], 0, v[238:239]
	global_load_lds_dwordx4 v[90:91], off
	s_add_u32 m0, s98, 0x7000
	v_lshl_add_u64 v[94:95], v[4:5], 0, v[238:239]
	global_load_lds_dwordx4 v[94:95], off
	s_mov_b32 s9, 0
	v_mov_b32_e32 v47, v46
	v_mov_b32_e32 v48, v46
	v_mov_b32_e32 v49, v46
	v_mov_b32_e32 v58, v46
	v_mov_b32_e32 v59, v46
	v_mov_b32_e32 v60, v46
	v_mov_b32_e32 v61, v46
	v_mov_b32_e32 v62, v46
	v_mov_b32_e32 v63, v46
	v_mov_b32_e32 v64, v46
	v_mov_b32_e32 v65, v46
	v_mov_b32_e32 v54, v46
	v_mov_b32_e32 v55, v46
	v_mov_b32_e32 v56, v46
	v_mov_b32_e32 v57, v46
	v_mov_b32_e32 v14, v46
	v_mov_b32_e32 v15, v46
	v_mov_b32_e32 v16, v46
	v_mov_b32_e32 v17, v46
	v_mov_b32_e32 v6, v46
	v_mov_b32_e32 v7, v46
	v_mov_b32_e32 v8, v46
	v_mov_b32_e32 v9, v46
	v_mov_b32_e32 v10, v46
	v_mov_b32_e32 v11, v46
	s_lshl_b64 s[12:13], s[6:7], 9
	v_lshl_add_u64 v[108:109], v[104:105], 0, s[16:17]
	v_lshl_add_u64 v[110:111], v[106:107], 0, s[14:15]
	v_mov_b32_e32 v12, v46
	v_mov_b32_e32 v13, v46
	v_mov_b32_e32 v50, v46
	v_mov_b32_e32 v51, v46
	v_mov_b32_e32 v52, v46
	v_mov_b32_e32 v53, v46
	v_mov_b32_e32 v42, v46
	v_mov_b32_e32 v43, v46
	v_mov_b32_e32 v44, v46
	v_mov_b32_e32 v45, v46
	v_mov_b32_e32 v30, v46
	v_mov_b32_e32 v31, v46
	v_mov_b32_e32 v32, v46
	v_mov_b32_e32 v33, v46
	v_mov_b32_e32 v34, v46
	v_mov_b32_e32 v35, v46
	v_mov_b32_e32 v36, v46
	v_mov_b32_e32 v37, v46
	v_mov_b32_e32 v38, v46
	v_mov_b32_e32 v39, v46
	v_mov_b32_e32 v40, v46
	v_mov_b32_e32 v41, v46
	v_mov_b32_e32 v26, v46
	v_mov_b32_e32 v27, v46
	v_mov_b32_e32 v28, v46
	v_mov_b32_e32 v29, v46
	v_mov_b32_e32 v22, v46
	v_mov_b32_e32 v23, v46
	v_mov_b32_e32 v24, v46
	v_mov_b32_e32 v25, v46
	v_mov_b32_e32 v18, v46
	v_mov_b32_e32 v19, v46
	v_mov_b32_e32 v20, v46
	v_mov_b32_e32 v21, v46
	v_mov_b32_e32 v2, v46
	v_mov_b32_e32 v3, v46
	v_mov_b32_e32 v4, v46
	v_mov_b32_e32 v5, v46
	s_waitcnt lgkmcnt(0)
	s_waitcnt vmcnt(0)
	s_barrier
	s_branch .LBB0_915
.LBB0_914:
	s_add_u32 s10, s10, 0x80
	s_addc_u32 s11, s11, 0
	s_add_i32 s9, s9, 1
	s_cmpk_lg_i32 s10, 0x400
	s_mov_b32 s27, s7
	s_waitcnt lgkmcnt(0)
	s_waitcnt vmcnt(0)
	s_barrier
	s_cbranch_scc0 .LBB0_921
.LBB0_915:
	s_cmp_gt_u32 s9, 6
	s_cselect_b64 s[14:15], -1, 0
	s_and_b64 vcc, exec, s[14:15]
	s_cbranch_vccnz .LBB0_917
	s_and_b32 s99, s27, 0x8000
	s_xor_b32 s99, s99, 0x8000
	s_add_u32 s99, s99, s98
	s_mov_b32 m0, s99
	v_lshl_add_u64 v[70:71], v[70:71], 0, v[242:243]
	global_load_lds_dwordx4 v[70:71], off
	s_add_u32 m0, s99, 0x1000
	v_lshl_add_u64 v[66:67], v[66:67], 0, v[242:243]
	global_load_lds_dwordx4 v[66:67], off
	s_add_u32 m0, s99, 0x2000
	v_lshl_add_u64 v[74:75], v[74:75], 0, v[242:243]
	global_load_lds_dwordx4 v[74:75], off
	s_add_u32 m0, s99, 0x3000
	v_lshl_add_u64 v[78:79], v[78:79], 0, v[242:243]
	global_load_lds_dwordx4 v[78:79], off
	s_add_u32 m0, s99, 0x4000
	v_lshl_add_u64 v[82:83], v[82:83], 0, v[242:243]
	global_load_lds_dwordx4 v[82:83], off
	s_add_u32 m0, s99, 0x5000
	v_lshl_add_u64 v[86:87], v[86:87], 0, v[242:243]
	global_load_lds_dwordx4 v[86:87], off
	s_add_u32 m0, s99, 0x6000
	v_lshl_add_u64 v[90:91], v[90:91], 0, v[242:243]
	global_load_lds_dwordx4 v[90:91], off
	s_add_u32 m0, s99, 0x7000
	v_lshl_add_u64 v[94:95], v[94:95], 0, v[242:243]
	global_load_lds_dwordx4 v[94:95], off

.LBB0_919:
	s_andn2_b64 vcc, exec, s[16:17]
	s_cbranch_vccnz .LBB0_914
	s_add_i32 s7, s27, 0x8000
	s_and_b32 s14, s7, 0x8000
	v_or_b32_e32 v124, s14, v114
	s_branch .LBB0_914
.LBB0_921:
	s_waitcnt vmcnt(7)
	v_lshl_add_u64 v[70:71], s[12:13], 1, v[100:101]
	v_add_co_u32_e32 v72, vcc, 0x8000, v70
	s_nop 1
	v_addc_co_u32_e32 v73, vcc, 0, v71, vcc
	s_waitcnt vmcnt(4)
	v_add_co_u32_e32 v78, vcc, 0x10000, v70
	s_barrier
	s_nop 0
	v_addc_co_u32_e32 v79, vcc, 0, v71, vcc
	s_add_u32 m0, s98, 0x1000
	v_lshl_add_u64 v[66:67], v[72:73], 0, v[238:239]
	global_load_lds_dwordx4 v[66:67], off
	s_add_u32 m0, s98, 0x2000
	v_lshl_add_u64 v[74:75], v[78:79], 0, v[238:239]
	global_load_lds_dwordx4 v[74:75], off
	v_add_co_u32_e32 v78, vcc, 0x18000, v70
	s_mov_b32 s7, 0
	s_nop 0
	v_addc_co_u32_e32 v79, vcc, 0, v71, vcc
	v_add_co_u32_e32 v86, vcc, 0x10000, v112
	s_mov_b32 m0, s98
	v_lshl_add_u64 v[70:71], v[70:71], 0, v[238:239]
	global_load_lds_dwordx4 v[70:71], off
	s_nop 0
	s_add_u32 m0, s98, 0x4000
	v_lshl_add_u64 v[82:83], v[112:113], 0, v[240:241]
	global_load_lds_dwordx4 v[82:83], off
	v_addc_co_u32_e32 v87, vcc, 0, v113, vcc
	v_add_co_u32_e32 v90, vcc, 0x20000, v112
	s_add_u32 m0, s98, 0x3000
	v_lshl_add_u64 v[78:79], v[78:79], 0, v[238:239]
	global_load_lds_dwordx4 v[78:79], off
	s_nop 0
	s_add_u32 m0, s98, 0x5000
	v_lshl_add_u64 v[86:87], v[86:87], 0, v[240:241]
	global_load_lds_dwordx4 v[86:87], off
	v_addc_co_u32_e32 v91, vcc, 0, v113, vcc
	v_add_co_u32_e32 v94, vcc, 0x30000, v112
	s_mov_b64 s[10:11], 0
	s_nop 0
	v_addc_co_u32_e32 v95, vcc, 0, v113, vcc
	s_add_u32 m0, s98, 0x6000
	v_lshl_add_u64 v[90:91], v[90:91], 0, v[240:241]
	global_load_lds_dwordx4 v[90:91], off
	s_nop 0
	s_add_u32 m0, s98, 0x7000
	v_lshl_add_u64 v[94:95], v[94:95], 0, v[240:241]
	global_load_lds_dwordx4 v[94:95], off
	s_mov_b32 s9, 0
	s_waitcnt lgkmcnt(0)
	s_waitcnt vmcnt(0)
	s_barrier
	s_branch .LBB0_923
.LBB0_922:
	s_add_u32 s10, s10, 0x80
	s_addc_u32 s11, s11, 0
	s_add_i32 s9, s9, 1
	s_cmpk_lg_i32 s10, 0x400
	s_mov_b32 s7, s12
	s_waitcnt lgkmcnt(0)
	s_waitcnt vmcnt(0)
	s_barrier
	s_cbranch_scc0 .LBB0_929
.LBB0_923:
	s_cmp_gt_u32 s9, 6
	s_cselect_b64 s[12:13], -1, 0
	s_and_b64 vcc, exec, s[12:13]
	s_cbranch_vccnz .LBB0_925
	s_and_b32 s99, s7, 0x8000
	s_xor_b32 s99, s99, 0x8000
	s_add_u32 s99, s99, s98
	s_mov_b32 m0, s99
	v_lshl_add_u64 v[70:71], v[70:71], 0, v[242:243]
	global_load_lds_dwordx4 v[70:71], off
	s_add_u32 m0, s99, 0x1000
	v_lshl_add_u64 v[66:67], v[66:67], 0, v[242:243]
	global_load_lds_dwordx4 v[66:67], off
	s_add_u32 m0, s99, 0x2000
	v_lshl_add_u64 v[74:75], v[74:75], 0, v[242:243]
	global_load_lds_dwordx4 v[74:75], off
	s_add_u32 m0, s99, 0x3000
	v_lshl_add_u64 v[78:79], v[78:79], 0, v[242:243]
	global_load_lds_dwordx4 v[78:79], off
	s_add_u32 m0, s99, 0x4000
	v_lshl_add_u64 v[82:83], v[82:83], 0, v[242:243]
	global_load_lds_dwordx4 v[82:83], off
	s_add_u32 m0, s99, 0x5000
	v_lshl_add_u64 v[86:87], v[86:87], 0, v[242:243]
	global_load_lds_dwordx4 v[86:87], off
	s_add_u32 m0, s99, 0x6000
	v_lshl_add_u64 v[90:91], v[90:91], 0, v[242:243]
	global_load_lds_dwordx4 v[90:91], off
	s_add_u32 m0, s99, 0x7000
	v_lshl_add_u64 v[94:95], v[94:95], 0, v[242:243]
	global_load_lds_dwordx4 v[94:95], off

.LBB0_927:
	s_andn2_b64 vcc, exec, s[14:15]
	s_cbranch_vccnz .LBB0_922
	s_add_i32 s12, s7, 0x8000
	s_and_b32 s7, s12, 0x8000
	v_or_b32_e32 v112, s7, v114
	s_branch .LBB0_922

.LBB0_942:
	s_lshl_b32 s6, s20, 9
	s_and_b32 s6, s6, 0x70000
	v_lshl_add_u64 v[106:107], v[104:105], 0, s[6:7]
	s_lshl_b32 s6, s16, 4
	s_lshl_b32 s9, s16, 7
	s_and_b32 s8, s6, 0xffffff80
	s_and_b32 s25, s9, 0x380
	s_ashr_i32 s9, s8, 31
	s_lshl_b64 s[10:11], s[8:9], 9
	v_lshl_add_u64 v[2:3], v[100:101], 0, s[10:11]
	v_add_co_u32_e32 v6, vcc, s22, v2
	s_lshl_b32 s6, s25, 9
	s_nop 0
	v_addc_co_u32_e32 v7, vcc, 0, v3, vcc
	v_add_co_u32_e32 v8, vcc, s23, v2
	s_nop 1
	v_addc_co_u32_e32 v9, vcc, 0, v3, vcc
	s_barrier
	s_add_u32 m0, s98, 0x1000
	v_lshl_add_u64 v[10:11], v[6:7], 0, v[238:239]
	global_load_lds_dwordx4 v[10:11], off
	s_add_u32 m0, s98, 0x2000
	v_lshl_add_u64 v[26:27], v[8:9], 0, v[238:239]
	global_load_lds_dwordx4 v[26:27], off
	v_add_co_u32_e32 v6, vcc, s24, v2
	v_lshl_add_u64 v[4:5], v[102:103], 0, s[6:7]
	s_nop 0
	v_addc_co_u32_e32 v7, vcc, 0, v3, vcc
	s_mov_b32 m0, s98
	v_lshl_add_u64 v[18:19], v[2:3], 0, v[238:239]
	global_load_lds_dwordx4 v[18:19], off
	s_add_u32 m0, s98, 0x4000
	v_lshl_add_u64 v[42:43], v[4:5], 0, v[238:239]
	global_load_lds_dwordx4 v[42:43], off
	v_add_co_u32_e32 v2, vcc, s22, v4
	s_and_b32 s12, s18, 0xffffff80
	s_nop 0
	v_addc_co_u32_e32 v3, vcc, 0, v5, vcc
	s_add_u32 m0, s98, 0x3000
	v_lshl_add_u64 v[38:39], v[6:7], 0, v[238:239]
	global_load_lds_dwordx4 v[38:39], off
	s_add_u32 m0, s98, 0x5000
	v_lshl_add_u64 v[46:47], v[2:3], 0, v[238:239]
	global_load_lds_dwordx4 v[46:47], off
	v_add_co_u32_e32 v2, vcc, s23, v4
	s_ashr_i32 s13, s12, 31
	s_nop 0
	v_addc_co_u32_e32 v3, vcc, 0, v5, vcc
	v_add_co_u32_e32 v4, vcc, 0xc000, v4
	s_lshl_b64 s[12:13], s[12:13], 9
	s_nop 0
	v_addc_co_u32_e32 v5, vcc, 0, v5, vcc
	s_add_u32 m0, s98, 0x6000
	v_lshl_add_u64 v[58:59], v[2:3], 0, v[238:239]
	global_load_lds_dwordx4 v[58:59], off
	s_add_u32 m0, s98, 0x7000
	v_lshl_add_u64 v[62:63], v[4:5], 0, v[238:239]
	global_load_lds_dwordx4 v[62:63], off
	s_mov_b64 s[10:11], 0
	s_mov_b32 s9, 0
	s_mov_b32 s6, 0
	v_mov_b32_e32 v2, 0
	v_mov_b32_e32 v3, v99
	v_mov_b32_e32 v4, v99
	v_mov_b32_e32 v5, v99
	v_mov_b32_e32 v6, 0
	v_mov_b32_e32 v7, v99
	v_mov_b32_e32 v8, v99
	v_mov_b32_e32 v9, v99
	v_mov_b32_e32 v14, 0
	v_mov_b32_e32 v15, v99
	v_mov_b32_e32 v16, v99
	v_mov_b32_e32 v17, v99
	v_mov_b32_e32 v22, 0
	v_mov_b32_e32 v23, v99
	v_mov_b32_e32 v24, v99
	v_mov_b32_e32 v25, v99
	v_mov_b32_e32 v30, 0
	v_mov_b32_e32 v31, v99
	v_mov_b32_e32 v32, v99
	v_mov_b32_e32 v33, v99
	v_mov_b32_e32 v34, 0
	v_mov_b32_e32 v35, v99
	v_lshl_add_u64 v[108:109], v[104:105], 0, s[12:13]
	v_mov_b32_e32 v36, v99
	v_mov_b32_e32 v37, v99
	v_mov_b32_e32 v50, 0
	v_mov_b32_e32 v51, v99
	v_mov_b32_e32 v52, v99
	v_mov_b32_e32 v53, v99
	v_mov_b32_e32 v54, 0
	v_mov_b32_e32 v55, v99
	v_mov_b32_e32 v56, v99
	v_mov_b32_e32 v57, v99
	v_mov_b32_e32 v66, 0
	v_mov_b32_e32 v67, v99
	v_mov_b32_e32 v68, v99
	v_mov_b32_e32 v69, v99
	v_mov_b32_e32 v70, 0
	v_mov_b32_e32 v71, v99
	v_mov_b32_e32 v72, v99
	v_mov_b32_e32 v73, v99
	v_mov_b32_e32 v74, 0
	v_mov_b32_e32 v75, v99
	v_mov_b32_e32 v76, v99
	v_mov_b32_e32 v77, v99
	v_mov_b32_e32 v78, 0
	v_mov_b32_e32 v79, v99
	v_mov_b32_e32 v80, v99
	v_mov_b32_e32 v81, v99
	v_mov_b32_e32 v82, 0
	v_mov_b32_e32 v83, v99
	v_mov_b32_e32 v84, v99
	v_mov_b32_e32 v85, v99
	v_mov_b32_e32 v86, 0
	v_mov_b32_e32 v87, v99
	v_mov_b32_e32 v88, v99
	v_mov_b32_e32 v89, v99
	v_mov_b32_e32 v90, 0
	v_mov_b32_e32 v91, v99
	v_mov_b32_e32 v92, v99
	v_mov_b32_e32 v93, v99
	v_mov_b32_e32 v94, 0
	v_mov_b32_e32 v95, v99
	v_mov_b32_e32 v96, v99
	v_mov_b32_e32 v97, v99
	s_waitcnt lgkmcnt(0)
	s_waitcnt vmcnt(0)
	s_barrier
	s_branch .LBB0_944
.LBB0_943:
	s_add_u32 s10, s10, 0x80
	s_addc_u32 s11, s11, 0
	s_add_i32 s6, s6, 1
	s_cmpk_lg_i32 s10, 0x200
	s_mov_b32 s9, s12
	s_waitcnt lgkmcnt(0)
	s_waitcnt vmcnt(0)
	s_barrier
	s_cbranch_scc0 .LBB0_941
.LBB0_944:
	s_cmp_gt_u32 s6, 2
	s_cselect_b64 s[12:13], -1, 0
	s_and_b64 vcc, exec, s[12:13]
	s_cbranch_vccnz .LBB0_946
	s_and_b32 s99, s9, 0x8000
	s_xor_b32 s99, s99, 0x8000
	s_add_u32 s99, s99, s98
	s_mov_b32 m0, s99
	v_lshl_add_u64 v[18:19], v[18:19], 0, v[242:243]
	global_load_lds_dwordx4 v[18:19], off
	s_add_u32 m0, s99, 0x1000
	v_lshl_add_u64 v[10:11], v[10:11], 0, v[242:243]
	global_load_lds_dwordx4 v[10:11], off
	s_add_u32 m0, s99, 0x2000
	v_lshl_add_u64 v[26:27], v[26:27], 0, v[242:243]
	global_load_lds_dwordx4 v[26:27], off
	s_add_u32 m0, s99, 0x3000
	v_lshl_add_u64 v[38:39], v[38:39], 0, v[242:243]
	global_load_lds_dwordx4 v[38:39], off
	s_add_u32 m0, s99, 0x4000
	v_lshl_add_u64 v[42:43], v[42:43], 0, v[242:243]
	global_load_lds_dwordx4 v[42:43], off
	s_add_u32 m0, s99, 0x5000
	v_lshl_add_u64 v[46:47], v[46:47], 0, v[242:243]
	global_load_lds_dwordx4 v[46:47], off
	s_add_u32 m0, s99, 0x6000
	v_lshl_add_u64 v[58:59], v[58:59], 0, v[242:243]
	global_load_lds_dwordx4 v[58:59], off
	s_add_u32 m0, s99, 0x7000
	v_lshl_add_u64 v[62:63], v[62:63], 0, v[242:243]
	global_load_lds_dwordx4 v[62:63], off

.LBB0_948:
	s_andn2_b64 vcc, exec, s[14:15]
	s_cbranch_vccnz .LBB0_943
	s_add_i32 s12, s9, 0x8000
	s_and_b32 s9, s12, 0x8000
	v_or_b32_e32 v98, s9, v110
	s_branch .LBB0_943

.LBB0_1014:
	s_lshl_b32 s8, s11, 7
	s_ashr_i32 s9, s8, 31
	s_lshl_b64 s[12:13], s[8:9], 11
	v_lshl_add_u64 v[98:99], v[114:115], 0, s[12:13]
	v_add_co_u32_e32 v4, vcc, s19, v98
	s_lshl_b32 s10, s10, 7
	s_nop 0
	v_addc_co_u32_e32 v5, vcc, 0, v99, vcc
	v_add_co_u32_e32 v6, vcc, s20, v98
	s_ashr_i32 s11, s10, 31
	s_nop 0
	v_addc_co_u32_e32 v7, vcc, 0, v99, vcc
	s_lshl_b64 s[14:15], s[10:11], 11
	s_barrier
	s_add_u32 m0, s98, 0x1000
	v_lshl_add_u64 v[46:47], v[4:5], 0, v[238:239]
	global_load_lds_dwordx4 v[46:47], off
	s_add_u32 m0, s98, 0x2000
	v_lshl_add_u64 v[62:63], v[6:7], 0, v[238:239]
	global_load_lds_dwordx4 v[62:63], off
	v_add_co_u32_e32 v4, vcc, s21, v98
	s_waitcnt lgkmcnt(0)
	v_lshl_add_u64 v[2:3], v[116:117], 0, s[14:15]
	v_addc_co_u32_e32 v5, vcc, 0, v99, vcc
	v_add_co_u32_e32 v6, vcc, s19, v2
	s_mov_b32 m0, s98
	v_lshl_add_u64 v[50:51], v[98:99], 0, v[238:239]
	global_load_lds_dwordx4 v[50:51], off
	s_add_u32 m0, s98, 0x4000
	v_lshl_add_u64 v[82:83], v[2:3], 0, v[238:239]
	global_load_lds_dwordx4 v[82:83], off
	v_addc_co_u32_e32 v7, vcc, 0, v3, vcc
	s_add_u32 m0, s98, 0x3000
	v_lshl_add_u64 v[66:67], v[4:5], 0, v[238:239]
	global_load_lds_dwordx4 v[66:67], off
	s_add_u32 m0, s98, 0x5000
	v_lshl_add_u64 v[86:87], v[6:7], 0, v[238:239]
	global_load_lds_dwordx4 v[86:87], off
	v_add_co_u32_e32 v4, vcc, s20, v2
	v_mov_b32_e32 v78, 0
	v_addc_co_u32_e32 v5, vcc, 0, v3, vcc
	v_add_co_u32_e32 v2, vcc, s21, v2
	s_mov_b32 s11, 0
	s_nop 0
	v_addc_co_u32_e32 v3, vcc, 0, v3, vcc
	s_add_u32 m0, s98, 0x6000
	v_lshl_add_u64 v[90:91], v[4:5], 0, v[238:239]
	global_load_lds_dwordx4 v[90:91], off
	s_add_u32 m0, s98, 0x7000
	v_lshl_add_u64 v[94:95], v[2:3], 0, v[238:239]
	global_load_lds_dwordx4 v[94:95], off
	s_mov_b64 s[12:13], 0
	s_mov_b32 s9, 0
	v_mov_b32_e32 v79, v78
	v_mov_b32_e32 v80, v78
	v_mov_b32_e32 v81, v78
	v_mov_b32_e32 v74, v78
	v_mov_b32_e32 v75, v78
	v_mov_b32_e32 v76, v78
	v_mov_b32_e32 v77, v78
	v_mov_b32_e32 v70, v78
	v_mov_b32_e32 v71, v78
	v_mov_b32_e32 v72, v78
	v_mov_b32_e32 v73, v78
	v_mov_b32_e32 v58, v78
	v_mov_b32_e32 v59, v78
	v_mov_b32_e32 v60, v78
	v_mov_b32_e32 v61, v78
	v_mov_b32_e32 v54, v78
	v_mov_b32_e32 v55, v78
	v_mov_b32_e32 v56, v78
	v_mov_b32_e32 v57, v78
	v_mov_b32_e32 v42, v78
	v_mov_b32_e32 v43, v78
	v_mov_b32_e32 v44, v78
	v_mov_b32_e32 v45, v78
	v_mov_b32_e32 v38, v78
	v_mov_b32_e32 v39, v78
	v_mov_b32_e32 v40, v78
	v_mov_b32_e32 v41, v78
	v_lshl_add_u64 v[100:101], v[118:119], 0, s[14:15]
	v_mov_b32_e32 v34, v78
	v_mov_b32_e32 v35, v78
	v_mov_b32_e32 v36, v78
	v_mov_b32_e32 v37, v78
	v_mov_b32_e32 v30, v78
	v_mov_b32_e32 v31, v78
	v_mov_b32_e32 v32, v78
	v_mov_b32_e32 v33, v78
	v_mov_b32_e32 v26, v78
	v_mov_b32_e32 v27, v78
	v_mov_b32_e32 v28, v78
	v_mov_b32_e32 v29, v78
	v_mov_b32_e32 v22, v78
	v_mov_b32_e32 v23, v78
	v_mov_b32_e32 v24, v78
	v_mov_b32_e32 v25, v78
	v_mov_b32_e32 v18, v78
	v_mov_b32_e32 v19, v78
	v_mov_b32_e32 v20, v78
	v_mov_b32_e32 v21, v78
	v_mov_b32_e32 v14, v78
	v_mov_b32_e32 v15, v78
	v_mov_b32_e32 v16, v78
	v_mov_b32_e32 v17, v78
	v_mov_b32_e32 v10, v78
	v_mov_b32_e32 v11, v78
	v_mov_b32_e32 v12, v78
	v_mov_b32_e32 v13, v78
	v_mov_b32_e32 v6, v78
	v_mov_b32_e32 v7, v78
	v_mov_b32_e32 v8, v78
	v_mov_b32_e32 v9, v78
	v_mov_b32_e32 v2, v78
	v_mov_b32_e32 v3, v78
	v_mov_b32_e32 v4, v78
	v_mov_b32_e32 v5, v78
	s_waitcnt lgkmcnt(0)
	s_waitcnt vmcnt(0)
	s_barrier
	s_branch .LBB0_1016
.LBB0_1015:
	s_add_u32 s12, s12, 0x80
	s_addc_u32 s13, s13, 0
	s_add_i32 s9, s9, 1
	s_cmpk_lg_i32 s12, 0x800
	s_mov_b32 s11, s14
	s_waitcnt lgkmcnt(0)
	s_waitcnt vmcnt(0)
	s_barrier
	s_cbranch_scc0 .LBB0_1022
.LBB0_1016:
	s_cmp_gt_u32 s9, 14
	s_cselect_b64 s[14:15], -1, 0
	s_and_b64 vcc, exec, s[14:15]
	s_cbranch_vccnz .LBB0_1018
	s_and_b32 s99, s11, 0x8000
	s_xor_b32 s99, s99, 0x8000
	s_add_u32 s99, s99, s98
	s_mov_b32 m0, s99
	v_lshl_add_u64 v[50:51], v[50:51], 0, v[242:243]
	global_load_lds_dwordx4 v[50:51], off
	s_add_u32 m0, s99, 0x1000
	v_lshl_add_u64 v[46:47], v[46:47], 0, v[242:243]
	global_load_lds_dwordx4 v[46:47], off
	s_add_u32 m0, s99, 0x2000
	v_lshl_add_u64 v[62:63], v[62:63], 0, v[242:243]
	global_load_lds_dwordx4 v[62:63], off
	s_add_u32 m0, s99, 0x3000
	v_lshl_add_u64 v[66:67], v[66:67], 0, v[242:243]
	global_load_lds_dwordx4 v[66:67], off
	s_add_u32 m0, s99, 0x4000
	v_lshl_add_u64 v[82:83], v[82:83], 0, v[242:243]
	global_load_lds_dwordx4 v[82:83], off
	s_add_u32 m0, s99, 0x5000
	v_lshl_add_u64 v[86:87], v[86:87], 0, v[242:243]
	global_load_lds_dwordx4 v[86:87], off
	s_add_u32 m0, s99, 0x6000
	v_lshl_add_u64 v[90:91], v[90:91], 0, v[242:243]
	global_load_lds_dwordx4 v[90:91], off
	s_add_u32 m0, s99, 0x7000
	v_lshl_add_u64 v[94:95], v[94:95], 0, v[242:243]
	global_load_lds_dwordx4 v[94:95], off

.LBB0_1020:
	s_andn2_b64 vcc, exec, s[16:17]
	s_cbranch_vccnz .LBB0_1015
	s_add_i32 s14, s11, 0x8000
	s_and_b32 s11, s14, 0x8000
	v_or_b32_e32 v102, s11, v128
	s_branch .LBB0_1015

.LBB0_1039:
	s_lshl_b32 s8, s11, 7
	s_ashr_i32 s9, s8, 31
	s_lshl_b64 s[12:13], s[8:9], 11
	v_lshl_add_u64 v[98:99], v[114:115], 0, s[12:13]
	v_add_co_u32_e32 v4, vcc, s21, v98
	s_lshl_b32 s10, s10, 7
	s_nop 0
	v_addc_co_u32_e32 v5, vcc, 0, v99, vcc
	v_add_co_u32_e32 v6, vcc, s22, v98
	s_ashr_i32 s11, s10, 31
	s_nop 0
	v_addc_co_u32_e32 v7, vcc, 0, v99, vcc
	s_lshl_b64 s[14:15], s[10:11], 11
	s_barrier
	s_add_u32 m0, s98, 0x1000
	v_lshl_add_u64 v[46:47], v[4:5], 0, v[238:239]
	global_load_lds_dwordx4 v[46:47], off
	s_add_u32 m0, s98, 0x2000
	v_lshl_add_u64 v[62:63], v[6:7], 0, v[238:239]
	global_load_lds_dwordx4 v[62:63], off
	v_add_co_u32_e32 v4, vcc, s23, v98
	s_waitcnt lgkmcnt(0)
	v_lshl_add_u64 v[2:3], v[116:117], 0, s[14:15]
	v_addc_co_u32_e32 v5, vcc, 0, v99, vcc
	v_add_co_u32_e32 v6, vcc, s21, v2
	s_mov_b32 m0, s98
	v_lshl_add_u64 v[50:51], v[98:99], 0, v[238:239]
	global_load_lds_dwordx4 v[50:51], off
	s_add_u32 m0, s98, 0x4000
	v_lshl_add_u64 v[82:83], v[2:3], 0, v[238:239]
	global_load_lds_dwordx4 v[82:83], off
	v_addc_co_u32_e32 v7, vcc, 0, v3, vcc
	s_add_u32 m0, s98, 0x3000
	v_lshl_add_u64 v[66:67], v[4:5], 0, v[238:239]
	global_load_lds_dwordx4 v[66:67], off
	s_add_u32 m0, s98, 0x5000
	v_lshl_add_u64 v[86:87], v[6:7], 0, v[238:239]
	global_load_lds_dwordx4 v[86:87], off
	v_add_co_u32_e32 v4, vcc, s22, v2
	v_mov_b32_e32 v78, 0
	v_addc_co_u32_e32 v5, vcc, 0, v3, vcc
	v_add_co_u32_e32 v2, vcc, s23, v2
	s_mov_b32 s11, 0
	s_nop 0
	v_addc_co_u32_e32 v3, vcc, 0, v3, vcc
	s_add_u32 m0, s98, 0x6000
	v_lshl_add_u64 v[90:91], v[4:5], 0, v[238:239]
	global_load_lds_dwordx4 v[90:91], off
	s_add_u32 m0, s98, 0x7000
	v_lshl_add_u64 v[94:95], v[2:3], 0, v[238:239]
	global_load_lds_dwordx4 v[94:95], off
	s_mov_b64 s[12:13], 0
	s_mov_b32 s9, 0
	v_mov_b32_e32 v79, v78
	v_mov_b32_e32 v80, v78
	v_mov_b32_e32 v81, v78
	v_mov_b32_e32 v74, v78
	v_mov_b32_e32 v75, v78
	v_mov_b32_e32 v76, v78
	v_mov_b32_e32 v77, v78
	v_mov_b32_e32 v70, v78
	v_mov_b32_e32 v71, v78
	v_mov_b32_e32 v72, v78
	v_mov_b32_e32 v73, v78
	v_mov_b32_e32 v58, v78
	v_mov_b32_e32 v59, v78
	v_mov_b32_e32 v60, v78
	v_mov_b32_e32 v61, v78
	v_mov_b32_e32 v54, v78
	v_mov_b32_e32 v55, v78
	v_mov_b32_e32 v56, v78
	v_mov_b32_e32 v57, v78
	v_mov_b32_e32 v42, v78
	v_mov_b32_e32 v43, v78
	v_mov_b32_e32 v44, v78
	v_mov_b32_e32 v45, v78
	v_mov_b32_e32 v38, v78
	v_mov_b32_e32 v39, v78
	v_mov_b32_e32 v40, v78
	v_mov_b32_e32 v41, v78
	v_lshl_add_u64 v[100:101], v[118:119], 0, s[14:15]
	v_mov_b32_e32 v34, v78
	v_mov_b32_e32 v35, v78
	v_mov_b32_e32 v36, v78
	v_mov_b32_e32 v37, v78
	v_mov_b32_e32 v30, v78
	v_mov_b32_e32 v31, v78
	v_mov_b32_e32 v32, v78
	v_mov_b32_e32 v33, v78
	v_mov_b32_e32 v26, v78
	v_mov_b32_e32 v27, v78
	v_mov_b32_e32 v28, v78
	v_mov_b32_e32 v29, v78
	v_mov_b32_e32 v22, v78
	v_mov_b32_e32 v23, v78
	v_mov_b32_e32 v24, v78
	v_mov_b32_e32 v25, v78
	v_mov_b32_e32 v18, v78
	v_mov_b32_e32 v19, v78
	v_mov_b32_e32 v20, v78
	v_mov_b32_e32 v21, v78
	v_mov_b32_e32 v14, v78
	v_mov_b32_e32 v15, v78
	v_mov_b32_e32 v16, v78
	v_mov_b32_e32 v17, v78
	v_mov_b32_e32 v10, v78
	v_mov_b32_e32 v11, v78
	v_mov_b32_e32 v12, v78
	v_mov_b32_e32 v13, v78
	v_mov_b32_e32 v6, v78
	v_mov_b32_e32 v7, v78
	v_mov_b32_e32 v8, v78
	v_mov_b32_e32 v9, v78
	v_mov_b32_e32 v2, v78
	v_mov_b32_e32 v3, v78
	v_mov_b32_e32 v4, v78
	v_mov_b32_e32 v5, v78
	s_waitcnt lgkmcnt(0)
	s_waitcnt vmcnt(0)
	s_barrier
	s_branch .LBB0_1041

.LBB0_1061:
	s_lshl_b32 s5, s59, 6
	s_lshl_b32 s4, s8, 7
	s_and_b32 s5, s5, 64
	s_or_b32 s4, s4, s5
	s_ashr_i32 s5, s4, 31
	s_lshl_b32 s6, s7, 7
	s_lshl_b64 s[8:9], s[4:5], 11
	s_add_u32 s8, s54, s8
	s_addc_u32 s9, s55, s9
	s_ashr_i32 s7, s6, 31
	s_lshl_b64 s[10:11], s[6:7], 11
	v_lshrrev_b32_e32 v8, 3, v0
	s_add_u32 s12, s54, s10
	v_lshlrev_b32_e32 v22, 11, v8
	v_mov_b32_e32 v23, 0
	v_lshlrev_b32_e32 v4, 4, v0
	s_addc_u32 s13, s55, s11
	s_waitcnt lgkmcnt(0)
	v_lshl_add_u64 v[2:3], s[8:9], 0, v[22:23]
	v_and_b32_e32 v4, 0x70, v4
	v_mov_b32_e32 v5, v23
	s_waitcnt vmcnt(9)
	v_lshl_add_u64 v[58:59], v[2:3], 0, v[4:5]
	v_lshl_add_u64 v[2:3], s[12:13], 0, v[22:23]
	s_mov_b32 s5, 0x10000
	v_lshl_add_u64 v[2:3], v[2:3], 0, v[4:5]
	v_add_co_u32_e32 v4, vcc, s5, v58
	s_mov_b32 s5, 0xf000000
	s_nop 0
	v_addc_co_u32_e32 v5, vcc, 0, v59, vcc
	s_barrier
	s_mov_b32 m0, s98
	v_lshl_add_u64 v[34:35], v[58:59], 0, v[238:239]
	global_load_lds_dwordx4 v[34:35], off
	s_add_u32 m0, s98, 0x1000
	v_lshl_add_u64 v[38:39], v[4:5], 0, v[238:239]
	global_load_lds_dwordx4 v[38:39], off
	v_add_co_u32_e32 v4, vcc, s5, v2
	s_mov_b32 s5, 0xf010000
	s_nop 0
	v_addc_co_u32_e32 v5, vcc, 0, v3, vcc
	v_add_co_u32_e32 v6, vcc, s5, v2
	s_mov_b32 s5, 0xf020000
	s_nop 0
	v_addc_co_u32_e32 v7, vcc, 0, v3, vcc
	s_add_u32 m0, s98, 0x4000
	v_lshl_add_u64 v[42:43], v[4:5], 0, v[238:239]
	global_load_lds_dwordx4 v[42:43], off
	s_add_u32 m0, s98, 0x5000
	v_lshl_add_u64 v[46:47], v[6:7], 0, v[238:239]
	global_load_lds_dwordx4 v[46:47], off
	v_add_co_u32_e32 v4, vcc, s5, v2
	s_mov_b32 s5, 0xf030000
	s_nop 0
	v_addc_co_u32_e32 v5, vcc, 0, v3, vcc
	v_add_co_u32_e32 v2, vcc, s5, v2
	v_lshlrev_b32_e32 v7, 8, v0
	s_nop 0
	v_addc_co_u32_e32 v3, vcc, 0, v3, vcc
	s_add_u32 m0, s98, 0x6000
	v_lshl_add_u64 v[50:51], v[4:5], 0, v[238:239]
	global_load_lds_dwordx4 v[50:51], off
	s_add_u32 m0, s98, 0x7000
	v_lshl_add_u64 v[54:55], v[2:3], 0, v[238:239]
	global_load_lds_dwordx4 v[54:55], off
	v_lshrrev_b32_e32 v2, 4, v0
	v_bfe_u32 v3, v0, 4, 2
	v_and_b32_e32 v4, 7, v0
	v_lshrrev_b32_e32 v5, 2, v0
	v_lshlrev_b32_e32 v6, 7, v0
	v_lshlrev_b32_e32 v9, 7, v8
	v_xor_b32_e32 v8, v8, v0
	v_and_b32_e32 v62, 32, v5
	v_bitop3_b32 v2, v2, v4, 3 bitop3:0x6c
	v_bitop3_b32 v3, v3, v4, 4 bitop3:0x36
	v_and_b32_e32 v5, 0xf800, v7
	v_lshlrev_b32_e32 v4, 4, v4
	s_movk_i32 s12, 0x70
	v_and_b32_e32 v64, 0x2780, v6
	v_lshlrev_b32_e32 v6, 4, v8
	v_and_or_b32 v63, v0, 15, v62
	v_lshlrev_b32_e32 v65, 4, v2
	v_lshlrev_b32_e32 v66, 4, v3
	v_or3_b32 v2, s10, v5, v4
	v_mov_b32_e32 v3, s11
	s_mov_b32 s7, 0
	s_mov_b64 s[8:9], 0
	s_mov_b32 s5, 0
	v_and_or_b32 v67, v6, s12, v9
	v_lshlrev_b32_e32 v68, 7, v63
	v_lshl_add_u64 v[60:61], s[54:55], 0, v[2:3]
	v_mov_b32_e32 v22, v23
	v_mov_b32_e32 v24, v23
	v_mov_b32_e32 v25, v23
	v_mov_b32_e32 v30, v23
	v_mov_b32_e32 v31, v23
	v_mov_b32_e32 v32, v23
	v_mov_b32_e32 v33, v23
	v_mov_b32_e32 v26, v23
	v_mov_b32_e32 v27, v23
	v_mov_b32_e32 v28, v23
	v_mov_b32_e32 v29, v23
	v_mov_b32_e32 v18, v23
	v_mov_b32_e32 v19, v23
	v_mov_b32_e32 v20, v23
	v_mov_b32_e32 v21, v23
	v_mov_b32_e32 v14, v23
	v_mov_b32_e32 v15, v23
	v_mov_b32_e32 v16, v23
	v_mov_b32_e32 v17, v23
	v_mov_b32_e32 v10, v23
	v_mov_b32_e32 v11, v23
	v_mov_b32_e32 v12, v23
	v_mov_b32_e32 v13, v23
	v_mov_b32_e32 v6, v23
	v_mov_b32_e32 v7, v23
	v_mov_b32_e32 v8, v23
	v_mov_b32_e32 v9, v23
	v_mov_b32_e32 v2, v23
	v_mov_b32_e32 v3, v23
	v_mov_b32_e32 v4, v23
	v_mov_b32_e32 v5, v23
	s_waitcnt lgkmcnt(0)
	s_waitcnt vmcnt(0)
	s_barrier
	s_branch .LBB0_1063
.LBB0_1062:
	s_add_u32 s8, s8, 0x80
	s_addc_u32 s9, s9, 0
	s_add_i32 s5, s5, 1
	s_cmpk_lg_i32 s8, 0x800
	s_mov_b32 s7, s10
	s_waitcnt lgkmcnt(0)
	s_waitcnt vmcnt(0)
	s_barrier
	s_cbranch_scc0 .LBB0_1069
.LBB0_1063:
	s_cmp_gt_u32 s5, 14
	s_cselect_b64 s[10:11], -1, 0
	s_and_b64 vcc, exec, s[10:11]
	s_cbranch_vccnz .LBB0_1065
	s_and_b32 s99, s7, 0x8000
	s_xor_b32 s99, s99, 0x8000
	s_add_u32 s99, s99, s98
	s_mov_b32 m0, s99
	v_lshl_add_u64 v[34:35], v[34:35], 0, v[242:243]
	global_load_lds_dwordx4 v[34:35], off
	s_add_u32 m0, s99, 0x1000
	v_lshl_add_u64 v[38:39], v[38:39], 0, v[242:243]
	global_load_lds_dwordx4 v[38:39], off
	s_add_u32 m0, s99, 0x4000
	v_lshl_add_u64 v[42:43], v[42:43], 0, v[242:243]
	global_load_lds_dwordx4 v[42:43], off
	s_add_u32 m0, s99, 0x5000
	v_lshl_add_u64 v[46:47], v[46:47], 0, v[242:243]
	global_load_lds_dwordx4 v[46:47], off
	s_add_u32 m0, s99, 0x6000
	v_lshl_add_u64 v[50:51], v[50:51], 0, v[242:243]
	global_load_lds_dwordx4 v[50:51], off
	s_add_u32 m0, s99, 0x7000
	v_lshl_add_u64 v[54:55], v[54:55], 0, v[242:243]
	global_load_lds_dwordx4 v[54:55], off

.LBB0_1067:
	s_andn2_b64 vcc, exec, s[12:13]
	s_cbranch_vccnz .LBB0_1062
	s_add_i32 s10, s7, 0x8000
	s_and_b32 s7, s10, 0x8000
	v_or_b32_e32 v69, s7, v67
	s_branch .LBB0_1062

.LBB0_1083:
	s_lshl_b32 s8, s11, 7
	s_ashr_i32 s9, s8, 31
	s_lshl_b64 s[12:13], s[8:9], 11
	v_lshl_add_u64 v[98:99], v[114:115], 0, s[12:13]
	v_add_co_u32_e32 v4, vcc, s20, v98
	s_lshl_b32 s10, s10, 7
	s_nop 0
	v_addc_co_u32_e32 v5, vcc, 0, v99, vcc
	v_add_co_u32_e32 v6, vcc, s21, v98
	s_ashr_i32 s11, s10, 31
	s_nop 0
	v_addc_co_u32_e32 v7, vcc, 0, v99, vcc
	s_lshl_b64 s[14:15], s[10:11], 11
	s_barrier
	s_add_u32 m0, s98, 0x1000
	v_lshl_add_u64 v[46:47], v[4:5], 0, v[238:239]
	global_load_lds_dwordx4 v[46:47], off
	s_add_u32 m0, s98, 0x2000
	v_lshl_add_u64 v[62:63], v[6:7], 0, v[238:239]
	global_load_lds_dwordx4 v[62:63], off
	v_add_co_u32_e32 v4, vcc, s22, v98
	s_waitcnt lgkmcnt(0)
	v_lshl_add_u64 v[2:3], v[116:117], 0, s[14:15]
	v_addc_co_u32_e32 v5, vcc, 0, v99, vcc
	v_add_co_u32_e32 v6, vcc, s20, v2
	s_mov_b32 m0, s98
	v_lshl_add_u64 v[50:51], v[98:99], 0, v[238:239]
	global_load_lds_dwordx4 v[50:51], off
	s_add_u32 m0, s98, 0x4000
	v_lshl_add_u64 v[82:83], v[2:3], 0, v[238:239]
	global_load_lds_dwordx4 v[82:83], off
	v_addc_co_u32_e32 v7, vcc, 0, v3, vcc
	s_add_u32 m0, s98, 0x3000
	v_lshl_add_u64 v[66:67], v[4:5], 0, v[238:239]
	global_load_lds_dwordx4 v[66:67], off
	s_add_u32 m0, s98, 0x5000
	v_lshl_add_u64 v[86:87], v[6:7], 0, v[238:239]
	global_load_lds_dwordx4 v[86:87], off
	v_add_co_u32_e32 v4, vcc, s21, v2
	v_mov_b32_e32 v78, 0
	v_addc_co_u32_e32 v5, vcc, 0, v3, vcc
	v_add_co_u32_e32 v2, vcc, s22, v2
	s_mov_b32 s11, 0
	s_nop 0
	v_addc_co_u32_e32 v3, vcc, 0, v3, vcc
	s_add_u32 m0, s98, 0x6000
	v_lshl_add_u64 v[90:91], v[4:5], 0, v[238:239]
	global_load_lds_dwordx4 v[90:91], off
	s_add_u32 m0, s98, 0x7000
	v_lshl_add_u64 v[94:95], v[2:3], 0, v[238:239]
	global_load_lds_dwordx4 v[94:95], off
	s_mov_b64 s[12:13], 0
	s_mov_b32 s9, 0
	v_mov_b32_e32 v79, v78
	v_mov_b32_e32 v80, v78
	v_mov_b32_e32 v81, v78
	v_mov_b32_e32 v74, v78
	v_mov_b32_e32 v75, v78
	v_mov_b32_e32 v76, v78
	v_mov_b32_e32 v77, v78
	v_mov_b32_e32 v70, v78
	v_mov_b32_e32 v71, v78
	v_mov_b32_e32 v72, v78
	v_mov_b32_e32 v73, v78
	v_mov_b32_e32 v58, v78
	v_mov_b32_e32 v59, v78
	v_mov_b32_e32 v60, v78
	v_mov_b32_e32 v61, v78
	v_mov_b32_e32 v54, v78
	v_mov_b32_e32 v55, v78
	v_mov_b32_e32 v56, v78
	v_mov_b32_e32 v57, v78
	v_mov_b32_e32 v42, v78
	v_mov_b32_e32 v43, v78
	v_mov_b32_e32 v44, v78
	v_mov_b32_e32 v45, v78
	v_mov_b32_e32 v38, v78
	v_mov_b32_e32 v39, v78
	v_mov_b32_e32 v40, v78
	v_mov_b32_e32 v41, v78
	v_lshl_add_u64 v[100:101], v[118:119], 0, s[14:15]
	v_mov_b32_e32 v34, v78
	v_mov_b32_e32 v35, v78
	v_mov_b32_e32 v36, v78
	v_mov_b32_e32 v37, v78
	v_mov_b32_e32 v30, v78
	v_mov_b32_e32 v31, v78
	v_mov_b32_e32 v32, v78
	v_mov_b32_e32 v33, v78
	v_mov_b32_e32 v26, v78
	v_mov_b32_e32 v27, v78
	v_mov_b32_e32 v28, v78
	v_mov_b32_e32 v29, v78
	v_mov_b32_e32 v22, v78
	v_mov_b32_e32 v23, v78
	v_mov_b32_e32 v24, v78
	v_mov_b32_e32 v25, v78
	v_mov_b32_e32 v18, v78
	v_mov_b32_e32 v19, v78
	v_mov_b32_e32 v20, v78
	v_mov_b32_e32 v21, v78
	v_mov_b32_e32 v14, v78
	v_mov_b32_e32 v15, v78
	v_mov_b32_e32 v16, v78
	v_mov_b32_e32 v17, v78
	v_mov_b32_e32 v10, v78
	v_mov_b32_e32 v11, v78
	v_mov_b32_e32 v12, v78
	v_mov_b32_e32 v13, v78
	v_mov_b32_e32 v6, v78
	v_mov_b32_e32 v7, v78
	v_mov_b32_e32 v8, v78
	v_mov_b32_e32 v9, v78
	v_mov_b32_e32 v2, v78
	v_mov_b32_e32 v3, v78
	v_mov_b32_e32 v4, v78
	v_mov_b32_e32 v5, v78
	s_waitcnt lgkmcnt(0)
	s_waitcnt vmcnt(0)
	s_barrier
	s_branch .LBB0_1085

	.amdhsa_kernel _Z4megaILin1EEv6Params
		.amdhsa_group_segment_fixed_size 65536
		.amdhsa_private_segment_fixed_size 0
		.amdhsa_kernarg_size 456
		.amdhsa_user_sgpr_count 2
		.amdhsa_user_sgpr_dispatch_ptr 0
		.amdhsa_user_sgpr_queue_ptr 0
		.amdhsa_user_sgpr_kernarg_segment_ptr 1
		.amdhsa_user_sgpr_dispatch_id 0
		.amdhsa_user_sgpr_kernarg_preload_length 0
		.amdhsa_user_sgpr_kernarg_preload_offset 0
		.amdhsa_user_sgpr_private_segment_size 0
		.amdhsa_uses_dynamic_stack 0
		.amdhsa_enable_private_segment 0
		.amdhsa_system_sgpr_workgroup_id_x 1
		.amdhsa_system_sgpr_workgroup_id_y 0
		.amdhsa_system_sgpr_workgroup_id_z 0
		.amdhsa_system_sgpr_workgroup_info 0
		.amdhsa_system_vgpr_workitem_id 0
		.amdhsa_next_free_vgpr 246
		.amdhsa_next_free_sgpr 102
		.amdhsa_accum_offset 248
		.amdhsa_reserve_vcc 1
		.amdhsa_float_round_mode_32 0
		.amdhsa_float_round_mode_16_64 0
		.amdhsa_float_denorm_mode_32 3
		.amdhsa_float_denorm_mode_16_64 3
		.amdhsa_dx10_clamp 1
		.amdhsa_ieee_mode 1
		.amdhsa_fp16_overflow 0
		.amdhsa_tg_split 0
		.amdhsa_exception_fp_ieee_invalid_op 0
		.amdhsa_exception_fp_denorm_src 0
		.amdhsa_exception_fp_ieee_div_zero 0
		.amdhsa_exception_fp_ieee_overflow 0
		.amdhsa_exception_fp_ieee_underflow 0
		.amdhsa_exception_fp_ieee_inexact 0
		.amdhsa_exception_int_div_zero 0
	.end_amdhsa_kernel

amdhsa.kernels:
  - .agpr_count:     0
    .args:
      - .offset:         0
        .size:           200
        .value_kind:     by_value
      - .offset:         200
        .size:           4
        .value_kind:     hidden_block_count_x
      - .offset:         204
        .size:           4
        .value_kind:     hidden_block_count_y
      - .offset:         208
        .size:           4
        .value_kind:     hidden_block_count_z
      - .offset:         212
        .size:           2
        .value_kind:     hidden_group_size_x
      - .offset:         214
        .size:           2
        .value_kind:     hidden_group_size_y
      - .offset:         216
        .size:           2
        .value_kind:     hidden_group_size_z
      - .offset:         218
        .size:           2
        .value_kind:     hidden_remainder_x
      - .offset:         220
        .size:           2
        .value_kind:     hidden_remainder_y
      - .offset:         222
        .size:           2
        .value_kind:     hidden_remainder_z
      - .offset:         240
        .size:           8
        .value_kind:     hidden_global_offset_x
      - .offset:         248
        .size:           8
        .value_kind:     hidden_global_offset_y
      - .offset:         256
        .size:           8
        .value_kind:     hidden_global_offset_z
      - .offset:         264
        .size:           2
        .value_kind:     hidden_grid_dims
    .group_segment_fixed_size: 65536
    .kernarg_segment_align: 8
    .kernarg_segment_size: 456
    .language:       OpenCL C
    .language_version:
      - 2
      - 0
    .max_flat_workgroup_size: 256
    .name:           _Z4megaILin1EEv6Params
    .private_segment_fixed_size: 0
    .sgpr_count:     108
    .sgpr_spill_count: 277
    .symbol:         _Z4megaILin1EEv6Params.kd
    .uniform_work_group_size: 1
    .uses_dynamic_stack: false
    .vgpr_count:     246
    .vgpr_spill_count: 0
    .wavefront_size: 64
